# gate epilogues of the two up-projection GEMMs rewritten: all gate/previous-value loads of a stage issued together several stages ahead (was two loads per wait); same float op sequence
# speedup vs baseline: 1.0158x; 1.0007x over previous
.LBB0_1103:
	v_lshl_add_u32 v144, s26, 8, v152
	v_lshl_or_b32 v145, s51, 8, v154
	s_add_u32 s52, s10, s16
	s_addc_u32 s53, s11, s17
	v_lshlrev_b32_e32 v145, 1, v145
	s_add_u32 s54, s52, 0x26000
	s_addc_u32 s55, s53, 0
	s_add_u32 s56, s52, 0x4c000
	s_addc_u32 s57, s53, 0
	s_add_u32 s58, s52, 0x72000
	s_addc_u32 s59, s53, 0
	s_add_u32 s60, s52, 0x130000
	s_addc_u32 s61, s53, 0
	s_add_u32 s62, s52, 0x156000
	s_addc_u32 s63, s53, 0
	s_add_u32 s66, s52, 0x17c000
	s_addc_u32 s67, s53, 0
	s_add_u32 s68, s52, 0x1a2000
	s_addc_u32 s69, s53, 0
	s_add_u32 s70, s8, 0x8000
	s_addc_u32 s71, s9, 0
	s_add_u32 s72, s8, 0x10000
	s_addc_u32 s73, s9, 0
	s_add_u32 s74, s8, 0x18000
	s_addc_u32 s75, s9, 0
	s_add_u32 s76, s8, 0x40000
	s_addc_u32 s77, s9, 0
	s_add_u32 s78, s8, 0x48000
	s_addc_u32 s79, s9, 0
	s_add_u32 s80, s8, 0x50000
	s_addc_u32 s81, s9, 0
	s_add_u32 s82, s8, 0x58000
	s_addc_u32 s83, s9, 0
	v_mad_u32_u24 v146, v144, s50, v145
	v_lshl_add_u32 v147, v144, 11, v145
	s_nop 1
	global_load_dwordx4 v[168:171], v146, s[52:53]
	global_load_dwordx4 v[172:175], v146, s[52:53] offset:256
	global_load_dwordx4 v[176:179], v146, s[54:55]
	global_load_dwordx4 v[180:183], v146, s[54:55] offset:256
	global_load_dwordx4 v[184:187], v146, s[56:57]
	global_load_dwordx4 v[188:191], v146, s[56:57] offset:256
	global_load_dwordx4 v[192:195], v146, s[58:59]
	global_load_dwordx4 v[196:199], v146, s[58:59] offset:256
	global_load_dwordx4 v[200:203], v146, s[60:61]
	global_load_dwordx4 v[204:207], v146, s[60:61] offset:256
	global_load_dwordx4 v[208:211], v146, s[62:63]
	global_load_dwordx4 v[212:215], v146, s[62:63] offset:256
	s_waitcnt vmcnt(8)
	v_lshlrev_b32_e32 v158, 16, v168
	v_and_b32_e32 v159, 0xffff0000, v168
	v_lshlrev_b32_e32 v160, 16, v169
	v_and_b32_e32 v161, 0xffff0000, v169
	v_lshlrev_b32_e32 v162, 16, v170
	v_and_b32_e32 v163, 0xffff0000, v170
	v_lshlrev_b32_e32 v164, 16, v171
	v_and_b32_e32 v165, 0xffff0000, v171
	v_mul_f32_e32 v158, 0xbfb8aa3b, v158
	v_mul_f32_e32 v159, 0xbfb8aa3b, v159
	v_mul_f32_e32 v160, 0xbfb8aa3b, v160
	v_mul_f32_e32 v161, 0xbfb8aa3b, v161
	v_mul_f32_e32 v162, 0xbfb8aa3b, v162
	v_mul_f32_e32 v163, 0xbfb8aa3b, v163
	v_mul_f32_e32 v164, 0xbfb8aa3b, v164
	v_mul_f32_e32 v165, 0xbfb8aa3b, v165
	v_exp_f32_e32 v158, v158
	v_exp_f32_e32 v159, v159
	v_exp_f32_e32 v160, v160
	v_exp_f32_e32 v161, v161
	v_exp_f32_e32 v162, v162
	v_exp_f32_e32 v163, v163
	v_exp_f32_e32 v164, v164
	v_exp_f32_e32 v165, v165
	v_add_f32_e32 v158, 1.0, v158
	v_add_f32_e32 v159, 1.0, v159
	v_add_f32_e32 v160, 1.0, v160
	v_add_f32_e32 v161, 1.0, v161
	v_add_f32_e32 v162, 1.0, v162
	v_add_f32_e32 v163, 1.0, v163
	v_add_f32_e32 v164, 1.0, v164
	v_add_f32_e32 v165, 1.0, v165
	v_rcp_f32_e32 v158, v158
	v_rcp_f32_e32 v159, v159
	v_rcp_f32_e32 v160, v160
	v_rcp_f32_e32 v161, v161
	v_rcp_f32_e32 v162, v162
	v_rcp_f32_e32 v163, v163
	v_rcp_f32_e32 v164, v164
	v_rcp_f32_e32 v165, v165
	s_nop 0
	v_pk_mul_f32 v[124:125], v[124:125], v[158:159]
	v_pk_mul_f32 v[126:127], v[126:127], v[160:161]
	v_pk_mul_f32 v[120:121], v[120:121], v[162:163]
	v_pk_mul_f32 v[122:123], v[122:123], v[164:165]
	v_cvt_pk_bf16_f32 v168, v124, v125
	v_cvt_pk_bf16_f32 v169, v126, v127
	v_cvt_pk_bf16_f32 v170, v120, v121
	v_cvt_pk_bf16_f32 v171, v122, v123
	global_store_dwordx4 v147, v[168:171], s[8:9]
	v_lshlrev_b32_e32 v158, 16, v172
	v_and_b32_e32 v159, 0xffff0000, v172
	v_lshlrev_b32_e32 v160, 16, v173
	v_and_b32_e32 v161, 0xffff0000, v173
	v_lshlrev_b32_e32 v162, 16, v174
	v_and_b32_e32 v163, 0xffff0000, v174
	v_lshlrev_b32_e32 v164, 16, v175
	v_and_b32_e32 v165, 0xffff0000, v175
	v_mul_f32_e32 v158, 0xbfb8aa3b, v158
	v_mul_f32_e32 v159, 0xbfb8aa3b, v159
	v_mul_f32_e32 v160, 0xbfb8aa3b, v160
	v_mul_f32_e32 v161, 0xbfb8aa3b, v161
	v_mul_f32_e32 v162, 0xbfb8aa3b, v162
	v_mul_f32_e32 v163, 0xbfb8aa3b, v163
	v_mul_f32_e32 v164, 0xbfb8aa3b, v164
	v_mul_f32_e32 v165, 0xbfb8aa3b, v165
	v_exp_f32_e32 v158, v158
	v_exp_f32_e32 v159, v159
	v_exp_f32_e32 v160, v160
	v_exp_f32_e32 v161, v161
	v_exp_f32_e32 v162, v162
	v_exp_f32_e32 v163, v163
	v_exp_f32_e32 v164, v164
	v_exp_f32_e32 v165, v165
	v_add_f32_e32 v158, 1.0, v158
	v_add_f32_e32 v159, 1.0, v159
	v_add_f32_e32 v160, 1.0, v160
	v_add_f32_e32 v161, 1.0, v161
	v_add_f32_e32 v162, 1.0, v162
	v_add_f32_e32 v163, 1.0, v163
	v_add_f32_e32 v164, 1.0, v164
	v_add_f32_e32 v165, 1.0, v165
	v_rcp_f32_e32 v158, v158
	v_rcp_f32_e32 v159, v159
	v_rcp_f32_e32 v160, v160
	v_rcp_f32_e32 v161, v161
	v_rcp_f32_e32 v162, v162
	v_rcp_f32_e32 v163, v163
	v_rcp_f32_e32 v164, v164
	v_rcp_f32_e32 v165, v165
	s_nop 0
	v_pk_mul_f32 v[116:117], v[116:117], v[158:159]
	v_pk_mul_f32 v[118:119], v[118:119], v[160:161]
	v_pk_mul_f32 v[112:113], v[112:113], v[162:163]
	v_pk_mul_f32 v[114:115], v[114:115], v[164:165]
	v_cvt_pk_bf16_f32 v172, v116, v117
	v_cvt_pk_bf16_f32 v173, v118, v119
	v_cvt_pk_bf16_f32 v174, v112, v113
	v_cvt_pk_bf16_f32 v175, v114, v115
	global_store_dwordx4 v147, v[172:175], s[8:9] offset:256
	v_lshlrev_b32_e32 v158, 16, v176
	v_and_b32_e32 v159, 0xffff0000, v176
	v_lshlrev_b32_e32 v160, 16, v177
	v_and_b32_e32 v161, 0xffff0000, v177
	v_lshlrev_b32_e32 v162, 16, v178
	v_and_b32_e32 v163, 0xffff0000, v178
	v_lshlrev_b32_e32 v164, 16, v179
	v_and_b32_e32 v165, 0xffff0000, v179
	v_mul_f32_e32 v158, 0xbfb8aa3b, v158
	v_mul_f32_e32 v159, 0xbfb8aa3b, v159
	v_mul_f32_e32 v160, 0xbfb8aa3b, v160
	v_mul_f32_e32 v161, 0xbfb8aa3b, v161
	v_mul_f32_e32 v162, 0xbfb8aa3b, v162
	v_mul_f32_e32 v163, 0xbfb8aa3b, v163
	v_mul_f32_e32 v164, 0xbfb8aa3b, v164
	v_mul_f32_e32 v165, 0xbfb8aa3b, v165
	v_exp_f32_e32 v158, v158
	v_exp_f32_e32 v159, v159
	v_exp_f32_e32 v160, v160
	v_exp_f32_e32 v161, v161
	v_exp_f32_e32 v162, v162
	v_exp_f32_e32 v163, v163
	v_exp_f32_e32 v164, v164
	v_exp_f32_e32 v165, v165
	v_add_f32_e32 v158, 1.0, v158
	v_add_f32_e32 v159, 1.0, v159
	v_add_f32_e32 v160, 1.0, v160
	v_add_f32_e32 v161, 1.0, v161
	v_add_f32_e32 v162, 1.0, v162
	v_add_f32_e32 v163, 1.0, v163
	v_add_f32_e32 v164, 1.0, v164
	v_add_f32_e32 v165, 1.0, v165
	v_rcp_f32_e32 v158, v158
	v_rcp_f32_e32 v159, v159
	v_rcp_f32_e32 v160, v160
	v_rcp_f32_e32 v161, v161
	v_rcp_f32_e32 v162, v162
	v_rcp_f32_e32 v163, v163
	v_rcp_f32_e32 v164, v164
	v_rcp_f32_e32 v165, v165
	s_nop 0
	v_pk_mul_f32 v[108:109], v[108:109], v[158:159]
	v_pk_mul_f32 v[110:111], v[110:111], v[160:161]
	v_pk_mul_f32 v[104:105], v[104:105], v[162:163]
	v_pk_mul_f32 v[106:107], v[106:107], v[164:165]
	v_cvt_pk_bf16_f32 v176, v108, v109
	v_cvt_pk_bf16_f32 v177, v110, v111
	v_cvt_pk_bf16_f32 v178, v104, v105
	v_cvt_pk_bf16_f32 v179, v106, v107
	global_store_dwordx4 v147, v[176:179], s[70:71]
	v_lshlrev_b32_e32 v158, 16, v180
	v_and_b32_e32 v159, 0xffff0000, v180
	v_lshlrev_b32_e32 v160, 16, v181
	v_and_b32_e32 v161, 0xffff0000, v181
	v_lshlrev_b32_e32 v162, 16, v182
	v_and_b32_e32 v163, 0xffff0000, v182
	v_lshlrev_b32_e32 v164, 16, v183
	v_and_b32_e32 v165, 0xffff0000, v183
	v_mul_f32_e32 v158, 0xbfb8aa3b, v158
	v_mul_f32_e32 v159, 0xbfb8aa3b, v159
	v_mul_f32_e32 v160, 0xbfb8aa3b, v160
	v_mul_f32_e32 v161, 0xbfb8aa3b, v161
	v_mul_f32_e32 v162, 0xbfb8aa3b, v162
	v_mul_f32_e32 v163, 0xbfb8aa3b, v163
	v_mul_f32_e32 v164, 0xbfb8aa3b, v164
	v_mul_f32_e32 v165, 0xbfb8aa3b, v165
	v_exp_f32_e32 v158, v158
	v_exp_f32_e32 v159, v159
	v_exp_f32_e32 v160, v160
	v_exp_f32_e32 v161, v161
	v_exp_f32_e32 v162, v162
	v_exp_f32_e32 v163, v163
	v_exp_f32_e32 v164, v164
	v_exp_f32_e32 v165, v165
	v_add_f32_e32 v158, 1.0, v158
	v_add_f32_e32 v159, 1.0, v159
	v_add_f32_e32 v160, 1.0, v160
	v_add_f32_e32 v161, 1.0, v161
	v_add_f32_e32 v162, 1.0, v162
	v_add_f32_e32 v163, 1.0, v163
	v_add_f32_e32 v164, 1.0, v164
	v_add_f32_e32 v165, 1.0, v165
	v_rcp_f32_e32 v158, v158
	v_rcp_f32_e32 v159, v159
	v_rcp_f32_e32 v160, v160
	v_rcp_f32_e32 v161, v161
	v_rcp_f32_e32 v162, v162
	v_rcp_f32_e32 v163, v163
	v_rcp_f32_e32 v164, v164
	v_rcp_f32_e32 v165, v165
	s_nop 0
	v_pk_mul_f32 v[100:101], v[100:101], v[158:159]
	v_pk_mul_f32 v[102:103], v[102:103], v[160:161]
	v_pk_mul_f32 v[96:97], v[96:97], v[162:163]
	v_pk_mul_f32 v[98:99], v[98:99], v[164:165]
	v_cvt_pk_bf16_f32 v180, v100, v101
	v_cvt_pk_bf16_f32 v181, v102, v103
	v_cvt_pk_bf16_f32 v182, v96, v97
	v_cvt_pk_bf16_f32 v183, v98, v99
	global_store_dwordx4 v147, v[180:183], s[70:71] offset:256
	s_nop 1
	global_load_dwordx4 v[168:171], v146, s[66:67]
	global_load_dwordx4 v[172:175], v146, s[66:67] offset:256
	global_load_dwordx4 v[176:179], v146, s[68:69]
	global_load_dwordx4 v[180:183], v146, s[68:69] offset:256
	s_waitcnt vmcnt(12)
	v_lshlrev_b32_e32 v158, 16, v184
	v_and_b32_e32 v159, 0xffff0000, v184
	v_lshlrev_b32_e32 v160, 16, v185
	v_and_b32_e32 v161, 0xffff0000, v185
	v_lshlrev_b32_e32 v162, 16, v186
	v_and_b32_e32 v163, 0xffff0000, v186
	v_lshlrev_b32_e32 v164, 16, v187
	v_and_b32_e32 v165, 0xffff0000, v187
	v_mul_f32_e32 v158, 0xbfb8aa3b, v158
	v_mul_f32_e32 v159, 0xbfb8aa3b, v159
	v_mul_f32_e32 v160, 0xbfb8aa3b, v160
	v_mul_f32_e32 v161, 0xbfb8aa3b, v161
	v_mul_f32_e32 v162, 0xbfb8aa3b, v162
	v_mul_f32_e32 v163, 0xbfb8aa3b, v163
	v_mul_f32_e32 v164, 0xbfb8aa3b, v164
	v_mul_f32_e32 v165, 0xbfb8aa3b, v165
	v_exp_f32_e32 v158, v158
	v_exp_f32_e32 v159, v159
	v_exp_f32_e32 v160, v160
	v_exp_f32_e32 v161, v161
	v_exp_f32_e32 v162, v162
	v_exp_f32_e32 v163, v163
	v_exp_f32_e32 v164, v164
	v_exp_f32_e32 v165, v165
	v_add_f32_e32 v158, 1.0, v158
	v_add_f32_e32 v159, 1.0, v159
	v_add_f32_e32 v160, 1.0, v160
	v_add_f32_e32 v161, 1.0, v161
	v_add_f32_e32 v162, 1.0, v162
	v_add_f32_e32 v163, 1.0, v163
	v_add_f32_e32 v164, 1.0, v164
	v_add_f32_e32 v165, 1.0, v165
	v_rcp_f32_e32 v158, v158
	v_rcp_f32_e32 v159, v159
	v_rcp_f32_e32 v160, v160
	v_rcp_f32_e32 v161, v161
	v_rcp_f32_e32 v162, v162
	v_rcp_f32_e32 v163, v163
	v_rcp_f32_e32 v164, v164
	v_rcp_f32_e32 v165, v165
	s_nop 0
	v_pk_mul_f32 v[92:93], v[92:93], v[158:159]
	v_pk_mul_f32 v[94:95], v[94:95], v[160:161]
	v_pk_mul_f32 v[88:89], v[88:89], v[162:163]
	v_pk_mul_f32 v[90:91], v[90:91], v[164:165]
	v_cvt_pk_bf16_f32 v184, v92, v93
	v_cvt_pk_bf16_f32 v185, v94, v95
	v_cvt_pk_bf16_f32 v186, v88, v89
	v_cvt_pk_bf16_f32 v187, v90, v91
	global_store_dwordx4 v147, v[184:187], s[72:73]
	v_lshlrev_b32_e32 v158, 16, v188
	v_and_b32_e32 v159, 0xffff0000, v188
	v_lshlrev_b32_e32 v160, 16, v189
	v_and_b32_e32 v161, 0xffff0000, v189
	v_lshlrev_b32_e32 v162, 16, v190
	v_and_b32_e32 v163, 0xffff0000, v190
	v_lshlrev_b32_e32 v164, 16, v191
	v_and_b32_e32 v165, 0xffff0000, v191
	v_mul_f32_e32 v158, 0xbfb8aa3b, v158
	v_mul_f32_e32 v159, 0xbfb8aa3b, v159
	v_mul_f32_e32 v160, 0xbfb8aa3b, v160
	v_mul_f32_e32 v161, 0xbfb8aa3b, v161
	v_mul_f32_e32 v162, 0xbfb8aa3b, v162
	v_mul_f32_e32 v163, 0xbfb8aa3b, v163
	v_mul_f32_e32 v164, 0xbfb8aa3b, v164
	v_mul_f32_e32 v165, 0xbfb8aa3b, v165
	v_exp_f32_e32 v158, v158
	v_exp_f32_e32 v159, v159
	v_exp_f32_e32 v160, v160
	v_exp_f32_e32 v161, v161
	v_exp_f32_e32 v162, v162
	v_exp_f32_e32 v163, v163
	v_exp_f32_e32 v164, v164
	v_exp_f32_e32 v165, v165
	v_add_f32_e32 v158, 1.0, v158
	v_add_f32_e32 v159, 1.0, v159
	v_add_f32_e32 v160, 1.0, v160
	v_add_f32_e32 v161, 1.0, v161
	v_add_f32_e32 v162, 1.0, v162
	v_add_f32_e32 v163, 1.0, v163
	v_add_f32_e32 v164, 1.0, v164
	v_add_f32_e32 v165, 1.0, v165
	v_rcp_f32_e32 v158, v158
	v_rcp_f32_e32 v159, v159
	v_rcp_f32_e32 v160, v160
	v_rcp_f32_e32 v161, v161
	v_rcp_f32_e32 v162, v162
	v_rcp_f32_e32 v163, v163
	v_rcp_f32_e32 v164, v164
	v_rcp_f32_e32 v165, v165
	s_nop 0
	v_pk_mul_f32 v[84:85], v[84:85], v[158:159]
	v_pk_mul_f32 v[86:87], v[86:87], v[160:161]
	v_pk_mul_f32 v[80:81], v[80:81], v[162:163]
	v_pk_mul_f32 v[82:83], v[82:83], v[164:165]
	v_cvt_pk_bf16_f32 v188, v84, v85
	v_cvt_pk_bf16_f32 v189, v86, v87
	v_cvt_pk_bf16_f32 v190, v80, v81
	v_cvt_pk_bf16_f32 v191, v82, v83
	global_store_dwordx4 v147, v[188:191], s[72:73] offset:256
	v_lshlrev_b32_e32 v158, 16, v192
	v_and_b32_e32 v159, 0xffff0000, v192
	v_lshlrev_b32_e32 v160, 16, v193
	v_and_b32_e32 v161, 0xffff0000, v193
	v_lshlrev_b32_e32 v162, 16, v194
	v_and_b32_e32 v163, 0xffff0000, v194
	v_lshlrev_b32_e32 v164, 16, v195
	v_and_b32_e32 v165, 0xffff0000, v195
	v_mul_f32_e32 v158, 0xbfb8aa3b, v158
	v_mul_f32_e32 v159, 0xbfb8aa3b, v159
	v_mul_f32_e32 v160, 0xbfb8aa3b, v160
	v_mul_f32_e32 v161, 0xbfb8aa3b, v161
	v_mul_f32_e32 v162, 0xbfb8aa3b, v162
	v_mul_f32_e32 v163, 0xbfb8aa3b, v163
	v_mul_f32_e32 v164, 0xbfb8aa3b, v164
	v_mul_f32_e32 v165, 0xbfb8aa3b, v165
	v_exp_f32_e32 v158, v158
	v_exp_f32_e32 v159, v159
	v_exp_f32_e32 v160, v160
	v_exp_f32_e32 v161, v161
	v_exp_f32_e32 v162, v162
	v_exp_f32_e32 v163, v163
	v_exp_f32_e32 v164, v164
	v_exp_f32_e32 v165, v165
	v_add_f32_e32 v158, 1.0, v158
	v_add_f32_e32 v159, 1.0, v159
	v_add_f32_e32 v160, 1.0, v160
	v_add_f32_e32 v161, 1.0, v161
	v_add_f32_e32 v162, 1.0, v162
	v_add_f32_e32 v163, 1.0, v163
	v_add_f32_e32 v164, 1.0, v164
	v_add_f32_e32 v165, 1.0, v165
	v_rcp_f32_e32 v158, v158
	v_rcp_f32_e32 v159, v159
	v_rcp_f32_e32 v160, v160
	v_rcp_f32_e32 v161, v161
	v_rcp_f32_e32 v162, v162
	v_rcp_f32_e32 v163, v163
	v_rcp_f32_e32 v164, v164
	v_rcp_f32_e32 v165, v165
	s_nop 0
	v_pk_mul_f32 v[76:77], v[76:77], v[158:159]
	v_pk_mul_f32 v[78:79], v[78:79], v[160:161]
	v_pk_mul_f32 v[72:73], v[72:73], v[162:163]
	v_pk_mul_f32 v[74:75], v[74:75], v[164:165]
	v_cvt_pk_bf16_f32 v192, v76, v77
	v_cvt_pk_bf16_f32 v193, v78, v79
	v_cvt_pk_bf16_f32 v194, v72, v73
	v_cvt_pk_bf16_f32 v195, v74, v75
	global_store_dwordx4 v147, v[192:195], s[74:75]
	v_lshlrev_b32_e32 v158, 16, v196
	v_and_b32_e32 v159, 0xffff0000, v196
	v_lshlrev_b32_e32 v160, 16, v197
	v_and_b32_e32 v161, 0xffff0000, v197
	v_lshlrev_b32_e32 v162, 16, v198
	v_and_b32_e32 v163, 0xffff0000, v198
	v_lshlrev_b32_e32 v164, 16, v199
	v_and_b32_e32 v165, 0xffff0000, v199
	v_mul_f32_e32 v158, 0xbfb8aa3b, v158
	v_mul_f32_e32 v159, 0xbfb8aa3b, v159
	v_mul_f32_e32 v160, 0xbfb8aa3b, v160
	v_mul_f32_e32 v161, 0xbfb8aa3b, v161
	v_mul_f32_e32 v162, 0xbfb8aa3b, v162
	v_mul_f32_e32 v163, 0xbfb8aa3b, v163
	v_mul_f32_e32 v164, 0xbfb8aa3b, v164
	v_mul_f32_e32 v165, 0xbfb8aa3b, v165
	v_exp_f32_e32 v158, v158
	v_exp_f32_e32 v159, v159
	v_exp_f32_e32 v160, v160
	v_exp_f32_e32 v161, v161
	v_exp_f32_e32 v162, v162
	v_exp_f32_e32 v163, v163
	v_exp_f32_e32 v164, v164
	v_exp_f32_e32 v165, v165
	v_add_f32_e32 v158, 1.0, v158
	v_add_f32_e32 v159, 1.0, v159
	v_add_f32_e32 v160, 1.0, v160
	v_add_f32_e32 v161, 1.0, v161
	v_add_f32_e32 v162, 1.0, v162
	v_add_f32_e32 v163, 1.0, v163
	v_add_f32_e32 v164, 1.0, v164
	v_add_f32_e32 v165, 1.0, v165
	v_rcp_f32_e32 v158, v158
	v_rcp_f32_e32 v159, v159
	v_rcp_f32_e32 v160, v160
	v_rcp_f32_e32 v161, v161
	v_rcp_f32_e32 v162, v162
	v_rcp_f32_e32 v163, v163
	v_rcp_f32_e32 v164, v164
	v_rcp_f32_e32 v165, v165
	s_nop 0
	v_pk_mul_f32 v[68:69], v[68:69], v[158:159]
	v_pk_mul_f32 v[70:71], v[70:71], v[160:161]
	v_pk_mul_f32 v[64:65], v[64:65], v[162:163]
	v_pk_mul_f32 v[66:67], v[66:67], v[164:165]
	v_cvt_pk_bf16_f32 v196, v68, v69
	v_cvt_pk_bf16_f32 v197, v70, v71
	v_cvt_pk_bf16_f32 v198, v64, v65
	v_cvt_pk_bf16_f32 v199, v66, v67
	global_store_dwordx4 v147, v[196:199], s[74:75] offset:256
	s_waitcnt vmcnt(12)
	v_lshlrev_b32_e32 v158, 16, v200
	v_and_b32_e32 v159, 0xffff0000, v200
	v_lshlrev_b32_e32 v160, 16, v201
	v_and_b32_e32 v161, 0xffff0000, v201
	v_lshlrev_b32_e32 v162, 16, v202
	v_and_b32_e32 v163, 0xffff0000, v202
	v_lshlrev_b32_e32 v164, 16, v203
	v_and_b32_e32 v165, 0xffff0000, v203
	v_mul_f32_e32 v158, 0xbfb8aa3b, v158
	v_mul_f32_e32 v159, 0xbfb8aa3b, v159
	v_mul_f32_e32 v160, 0xbfb8aa3b, v160
	v_mul_f32_e32 v161, 0xbfb8aa3b, v161
	v_mul_f32_e32 v162, 0xbfb8aa3b, v162
	v_mul_f32_e32 v163, 0xbfb8aa3b, v163
	v_mul_f32_e32 v164, 0xbfb8aa3b, v164
	v_mul_f32_e32 v165, 0xbfb8aa3b, v165
	v_exp_f32_e32 v158, v158
	v_exp_f32_e32 v159, v159
	v_exp_f32_e32 v160, v160
	v_exp_f32_e32 v161, v161
	v_exp_f32_e32 v162, v162
	v_exp_f32_e32 v163, v163
	v_exp_f32_e32 v164, v164
	v_exp_f32_e32 v165, v165
	v_add_f32_e32 v158, 1.0, v158
	v_add_f32_e32 v159, 1.0, v159
	v_add_f32_e32 v160, 1.0, v160
	v_add_f32_e32 v161, 1.0, v161
	v_add_f32_e32 v162, 1.0, v162
	v_add_f32_e32 v163, 1.0, v163
	v_add_f32_e32 v164, 1.0, v164
	v_add_f32_e32 v165, 1.0, v165
	v_rcp_f32_e32 v158, v158
	v_rcp_f32_e32 v159, v159
	v_rcp_f32_e32 v160, v160
	v_rcp_f32_e32 v161, v161
	v_rcp_f32_e32 v162, v162
	v_rcp_f32_e32 v163, v163
	v_rcp_f32_e32 v164, v164
	v_rcp_f32_e32 v165, v165
	s_nop 0
	v_pk_mul_f32 v[60:61], v[60:61], v[158:159]
	v_pk_mul_f32 v[62:63], v[62:63], v[160:161]
	v_pk_mul_f32 v[56:57], v[56:57], v[162:163]
	v_pk_mul_f32 v[58:59], v[58:59], v[164:165]
	v_cvt_pk_bf16_f32 v200, v60, v61
	v_cvt_pk_bf16_f32 v201, v62, v63
	v_cvt_pk_bf16_f32 v202, v56, v57
	v_cvt_pk_bf16_f32 v203, v58, v59
	global_store_dwordx4 v147, v[200:203], s[76:77]
	v_lshlrev_b32_e32 v158, 16, v204
	v_and_b32_e32 v159, 0xffff0000, v204
	v_lshlrev_b32_e32 v160, 16, v205
	v_and_b32_e32 v161, 0xffff0000, v205
	v_lshlrev_b32_e32 v162, 16, v206
	v_and_b32_e32 v163, 0xffff0000, v206
	v_lshlrev_b32_e32 v164, 16, v207
	v_and_b32_e32 v165, 0xffff0000, v207
	v_mul_f32_e32 v158, 0xbfb8aa3b, v158
	v_mul_f32_e32 v159, 0xbfb8aa3b, v159
	v_mul_f32_e32 v160, 0xbfb8aa3b, v160
	v_mul_f32_e32 v161, 0xbfb8aa3b, v161
	v_mul_f32_e32 v162, 0xbfb8aa3b, v162
	v_mul_f32_e32 v163, 0xbfb8aa3b, v163
	v_mul_f32_e32 v164, 0xbfb8aa3b, v164
	v_mul_f32_e32 v165, 0xbfb8aa3b, v165
	v_exp_f32_e32 v158, v158
	v_exp_f32_e32 v159, v159
	v_exp_f32_e32 v160, v160
	v_exp_f32_e32 v161, v161
	v_exp_f32_e32 v162, v162
	v_exp_f32_e32 v163, v163
	v_exp_f32_e32 v164, v164
	v_exp_f32_e32 v165, v165
	v_add_f32_e32 v158, 1.0, v158
	v_add_f32_e32 v159, 1.0, v159
	v_add_f32_e32 v160, 1.0, v160
	v_add_f32_e32 v161, 1.0, v161
	v_add_f32_e32 v162, 1.0, v162
	v_add_f32_e32 v163, 1.0, v163
	v_add_f32_e32 v164, 1.0, v164
	v_add_f32_e32 v165, 1.0, v165
	v_rcp_f32_e32 v158, v158
	v_rcp_f32_e32 v159, v159
	v_rcp_f32_e32 v160, v160
	v_rcp_f32_e32 v161, v161
	v_rcp_f32_e32 v162, v162
	v_rcp_f32_e32 v163, v163
	v_rcp_f32_e32 v164, v164
	v_rcp_f32_e32 v165, v165
	s_nop 0
	v_pk_mul_f32 v[52:53], v[52:53], v[158:159]
	v_pk_mul_f32 v[54:55], v[54:55], v[160:161]
	v_pk_mul_f32 v[48:49], v[48:49], v[162:163]
	v_pk_mul_f32 v[50:51], v[50:51], v[164:165]
	v_cvt_pk_bf16_f32 v204, v52, v53
	v_cvt_pk_bf16_f32 v205, v54, v55
	v_cvt_pk_bf16_f32 v206, v48, v49
	v_cvt_pk_bf16_f32 v207, v50, v51
	global_store_dwordx4 v147, v[204:207], s[76:77] offset:256
	v_lshlrev_b32_e32 v158, 16, v208
	v_and_b32_e32 v159, 0xffff0000, v208
	v_lshlrev_b32_e32 v160, 16, v209
	v_and_b32_e32 v161, 0xffff0000, v209
	v_lshlrev_b32_e32 v162, 16, v210
	v_and_b32_e32 v163, 0xffff0000, v210
	v_lshlrev_b32_e32 v164, 16, v211
	v_and_b32_e32 v165, 0xffff0000, v211
	v_mul_f32_e32 v158, 0xbfb8aa3b, v158
	v_mul_f32_e32 v159, 0xbfb8aa3b, v159
	v_mul_f32_e32 v160, 0xbfb8aa3b, v160
	v_mul_f32_e32 v161, 0xbfb8aa3b, v161
	v_mul_f32_e32 v162, 0xbfb8aa3b, v162
	v_mul_f32_e32 v163, 0xbfb8aa3b, v163
	v_mul_f32_e32 v164, 0xbfb8aa3b, v164
	v_mul_f32_e32 v165, 0xbfb8aa3b, v165
	v_exp_f32_e32 v158, v158
	v_exp_f32_e32 v159, v159
	v_exp_f32_e32 v160, v160
	v_exp_f32_e32 v161, v161
	v_exp_f32_e32 v162, v162
	v_exp_f32_e32 v163, v163
	v_exp_f32_e32 v164, v164
	v_exp_f32_e32 v165, v165
	v_add_f32_e32 v158, 1.0, v158
	v_add_f32_e32 v159, 1.0, v159
	v_add_f32_e32 v160, 1.0, v160
	v_add_f32_e32 v161, 1.0, v161
	v_add_f32_e32 v162, 1.0, v162
	v_add_f32_e32 v163, 1.0, v163
	v_add_f32_e32 v164, 1.0, v164
	v_add_f32_e32 v165, 1.0, v165
	v_rcp_f32_e32 v158, v158
	v_rcp_f32_e32 v159, v159
	v_rcp_f32_e32 v160, v160
	v_rcp_f32_e32 v161, v161
	v_rcp_f32_e32 v162, v162
	v_rcp_f32_e32 v163, v163
	v_rcp_f32_e32 v164, v164
	v_rcp_f32_e32 v165, v165
	s_nop 0
	v_pk_mul_f32 v[44:45], v[44:45], v[158:159]
	v_pk_mul_f32 v[46:47], v[46:47], v[160:161]
	v_pk_mul_f32 v[40:41], v[40:41], v[162:163]
	v_pk_mul_f32 v[42:43], v[42:43], v[164:165]
	v_cvt_pk_bf16_f32 v208, v44, v45
	v_cvt_pk_bf16_f32 v209, v46, v47
	v_cvt_pk_bf16_f32 v210, v40, v41
	v_cvt_pk_bf16_f32 v211, v42, v43
	global_store_dwordx4 v147, v[208:211], s[78:79]
	v_lshlrev_b32_e32 v158, 16, v212
	v_and_b32_e32 v159, 0xffff0000, v212
	v_lshlrev_b32_e32 v160, 16, v213
	v_and_b32_e32 v161, 0xffff0000, v213
	v_lshlrev_b32_e32 v162, 16, v214
	v_and_b32_e32 v163, 0xffff0000, v214
	v_lshlrev_b32_e32 v164, 16, v215
	v_and_b32_e32 v165, 0xffff0000, v215
	v_mul_f32_e32 v158, 0xbfb8aa3b, v158
	v_mul_f32_e32 v159, 0xbfb8aa3b, v159
	v_mul_f32_e32 v160, 0xbfb8aa3b, v160
	v_mul_f32_e32 v161, 0xbfb8aa3b, v161
	v_mul_f32_e32 v162, 0xbfb8aa3b, v162
	v_mul_f32_e32 v163, 0xbfb8aa3b, v163
	v_mul_f32_e32 v164, 0xbfb8aa3b, v164
	v_mul_f32_e32 v165, 0xbfb8aa3b, v165
	v_exp_f32_e32 v158, v158
	v_exp_f32_e32 v159, v159
	v_exp_f32_e32 v160, v160
	v_exp_f32_e32 v161, v161
	v_exp_f32_e32 v162, v162
	v_exp_f32_e32 v163, v163
	v_exp_f32_e32 v164, v164
	v_exp_f32_e32 v165, v165
	v_add_f32_e32 v158, 1.0, v158
	v_add_f32_e32 v159, 1.0, v159
	v_add_f32_e32 v160, 1.0, v160
	v_add_f32_e32 v161, 1.0, v161
	v_add_f32_e32 v162, 1.0, v162
	v_add_f32_e32 v163, 1.0, v163
	v_add_f32_e32 v164, 1.0, v164
	v_add_f32_e32 v165, 1.0, v165
	v_rcp_f32_e32 v158, v158
	v_rcp_f32_e32 v159, v159
	v_rcp_f32_e32 v160, v160
	v_rcp_f32_e32 v161, v161
	v_rcp_f32_e32 v162, v162
	v_rcp_f32_e32 v163, v163
	v_rcp_f32_e32 v164, v164
	v_rcp_f32_e32 v165, v165
	s_nop 0
	v_pk_mul_f32 v[36:37], v[36:37], v[158:159]
	v_pk_mul_f32 v[38:39], v[38:39], v[160:161]
	v_pk_mul_f32 v[32:33], v[32:33], v[162:163]
	v_pk_mul_f32 v[34:35], v[34:35], v[164:165]
	v_cvt_pk_bf16_f32 v212, v36, v37
	v_cvt_pk_bf16_f32 v213, v38, v39
	v_cvt_pk_bf16_f32 v214, v32, v33
	v_cvt_pk_bf16_f32 v215, v34, v35
	global_store_dwordx4 v147, v[212:215], s[78:79] offset:256
	s_waitcnt vmcnt(8)
	v_lshlrev_b32_e32 v158, 16, v168
	v_and_b32_e32 v159, 0xffff0000, v168
	v_lshlrev_b32_e32 v160, 16, v169
	v_and_b32_e32 v161, 0xffff0000, v169
	v_lshlrev_b32_e32 v162, 16, v170
	v_and_b32_e32 v163, 0xffff0000, v170
	v_lshlrev_b32_e32 v164, 16, v171
	v_and_b32_e32 v165, 0xffff0000, v171
	v_mul_f32_e32 v158, 0xbfb8aa3b, v158
	v_mul_f32_e32 v159, 0xbfb8aa3b, v159
	v_mul_f32_e32 v160, 0xbfb8aa3b, v160
	v_mul_f32_e32 v161, 0xbfb8aa3b, v161
	v_mul_f32_e32 v162, 0xbfb8aa3b, v162
	v_mul_f32_e32 v163, 0xbfb8aa3b, v163
	v_mul_f32_e32 v164, 0xbfb8aa3b, v164
	v_mul_f32_e32 v165, 0xbfb8aa3b, v165
	v_exp_f32_e32 v158, v158
	v_exp_f32_e32 v159, v159
	v_exp_f32_e32 v160, v160
	v_exp_f32_e32 v161, v161
	v_exp_f32_e32 v162, v162
	v_exp_f32_e32 v163, v163
	v_exp_f32_e32 v164, v164
	v_exp_f32_e32 v165, v165
	v_add_f32_e32 v158, 1.0, v158
	v_add_f32_e32 v159, 1.0, v159
	v_add_f32_e32 v160, 1.0, v160
	v_add_f32_e32 v161, 1.0, v161
	v_add_f32_e32 v162, 1.0, v162
	v_add_f32_e32 v163, 1.0, v163
	v_add_f32_e32 v164, 1.0, v164
	v_add_f32_e32 v165, 1.0, v165
	v_rcp_f32_e32 v158, v158
	v_rcp_f32_e32 v159, v159
	v_rcp_f32_e32 v160, v160
	v_rcp_f32_e32 v161, v161
	v_rcp_f32_e32 v162, v162
	v_rcp_f32_e32 v163, v163
	v_rcp_f32_e32 v164, v164
	v_rcp_f32_e32 v165, v165
	s_nop 0
	v_pk_mul_f32 v[28:29], v[28:29], v[158:159]
	v_pk_mul_f32 v[30:31], v[30:31], v[160:161]
	v_pk_mul_f32 v[24:25], v[24:25], v[162:163]
	v_pk_mul_f32 v[26:27], v[26:27], v[164:165]
	v_cvt_pk_bf16_f32 v168, v28, v29
	v_cvt_pk_bf16_f32 v169, v30, v31
	v_cvt_pk_bf16_f32 v170, v24, v25
	v_cvt_pk_bf16_f32 v171, v26, v27
	global_store_dwordx4 v147, v[168:171], s[80:81]
	v_lshlrev_b32_e32 v158, 16, v172
	v_and_b32_e32 v159, 0xffff0000, v172
	v_lshlrev_b32_e32 v160, 16, v173
	v_and_b32_e32 v161, 0xffff0000, v173
	v_lshlrev_b32_e32 v162, 16, v174
	v_and_b32_e32 v163, 0xffff0000, v174
	v_lshlrev_b32_e32 v164, 16, v175
	v_and_b32_e32 v165, 0xffff0000, v175
	v_mul_f32_e32 v158, 0xbfb8aa3b, v158
	v_mul_f32_e32 v159, 0xbfb8aa3b, v159
	v_mul_f32_e32 v160, 0xbfb8aa3b, v160
	v_mul_f32_e32 v161, 0xbfb8aa3b, v161
	v_mul_f32_e32 v162, 0xbfb8aa3b, v162
	v_mul_f32_e32 v163, 0xbfb8aa3b, v163
	v_mul_f32_e32 v164, 0xbfb8aa3b, v164
	v_mul_f32_e32 v165, 0xbfb8aa3b, v165
	v_exp_f32_e32 v158, v158
	v_exp_f32_e32 v159, v159
	v_exp_f32_e32 v160, v160
	v_exp_f32_e32 v161, v161
	v_exp_f32_e32 v162, v162
	v_exp_f32_e32 v163, v163
	v_exp_f32_e32 v164, v164
	v_exp_f32_e32 v165, v165
	v_add_f32_e32 v158, 1.0, v158
	v_add_f32_e32 v159, 1.0, v159
	v_add_f32_e32 v160, 1.0, v160
	v_add_f32_e32 v161, 1.0, v161
	v_add_f32_e32 v162, 1.0, v162
	v_add_f32_e32 v163, 1.0, v163
	v_add_f32_e32 v164, 1.0, v164
	v_add_f32_e32 v165, 1.0, v165
	v_rcp_f32_e32 v158, v158
	v_rcp_f32_e32 v159, v159
	v_rcp_f32_e32 v160, v160
	v_rcp_f32_e32 v161, v161
	v_rcp_f32_e32 v162, v162
	v_rcp_f32_e32 v163, v163
	v_rcp_f32_e32 v164, v164
	v_rcp_f32_e32 v165, v165
	s_nop 0
	v_pk_mul_f32 v[20:21], v[20:21], v[158:159]
	v_pk_mul_f32 v[22:23], v[22:23], v[160:161]
	v_pk_mul_f32 v[16:17], v[16:17], v[162:163]
	v_pk_mul_f32 v[18:19], v[18:19], v[164:165]
	v_cvt_pk_bf16_f32 v172, v20, v21
	v_cvt_pk_bf16_f32 v173, v22, v23
	v_cvt_pk_bf16_f32 v174, v16, v17
	v_cvt_pk_bf16_f32 v175, v18, v19
	global_store_dwordx4 v147, v[172:175], s[80:81] offset:256
	v_lshlrev_b32_e32 v158, 16, v176
	v_and_b32_e32 v159, 0xffff0000, v176
	v_lshlrev_b32_e32 v160, 16, v177
	v_and_b32_e32 v161, 0xffff0000, v177
	v_lshlrev_b32_e32 v162, 16, v178
	v_and_b32_e32 v163, 0xffff0000, v178
	v_lshlrev_b32_e32 v164, 16, v179
	v_and_b32_e32 v165, 0xffff0000, v179
	v_mul_f32_e32 v158, 0xbfb8aa3b, v158
	v_mul_f32_e32 v159, 0xbfb8aa3b, v159
	v_mul_f32_e32 v160, 0xbfb8aa3b, v160
	v_mul_f32_e32 v161, 0xbfb8aa3b, v161
	v_mul_f32_e32 v162, 0xbfb8aa3b, v162
	v_mul_f32_e32 v163, 0xbfb8aa3b, v163
	v_mul_f32_e32 v164, 0xbfb8aa3b, v164
	v_mul_f32_e32 v165, 0xbfb8aa3b, v165
	v_exp_f32_e32 v158, v158
	v_exp_f32_e32 v159, v159
	v_exp_f32_e32 v160, v160
	v_exp_f32_e32 v161, v161
	v_exp_f32_e32 v162, v162
	v_exp_f32_e32 v163, v163
	v_exp_f32_e32 v164, v164
	v_exp_f32_e32 v165, v165
	v_add_f32_e32 v158, 1.0, v158
	v_add_f32_e32 v159, 1.0, v159
	v_add_f32_e32 v160, 1.0, v160
	v_add_f32_e32 v161, 1.0, v161
	v_add_f32_e32 v162, 1.0, v162
	v_add_f32_e32 v163, 1.0, v163
	v_add_f32_e32 v164, 1.0, v164
	v_add_f32_e32 v165, 1.0, v165
	v_rcp_f32_e32 v158, v158
	v_rcp_f32_e32 v159, v159
	v_rcp_f32_e32 v160, v160
	v_rcp_f32_e32 v161, v161
	v_rcp_f32_e32 v162, v162
	v_rcp_f32_e32 v163, v163
	v_rcp_f32_e32 v164, v164
	v_rcp_f32_e32 v165, v165
	s_nop 0
	v_pk_mul_f32 v[12:13], v[12:13], v[158:159]
	v_pk_mul_f32 v[14:15], v[14:15], v[160:161]
	v_pk_mul_f32 v[8:9], v[8:9], v[162:163]
	v_pk_mul_f32 v[10:11], v[10:11], v[164:165]
	v_cvt_pk_bf16_f32 v176, v12, v13
	v_cvt_pk_bf16_f32 v177, v14, v15
	v_cvt_pk_bf16_f32 v178, v8, v9
	v_cvt_pk_bf16_f32 v179, v10, v11
	global_store_dwordx4 v147, v[176:179], s[82:83]
	v_lshlrev_b32_e32 v158, 16, v180
	v_and_b32_e32 v159, 0xffff0000, v180
	v_lshlrev_b32_e32 v160, 16, v181
	v_and_b32_e32 v161, 0xffff0000, v181
	v_lshlrev_b32_e32 v162, 16, v182
	v_and_b32_e32 v163, 0xffff0000, v182
	v_lshlrev_b32_e32 v164, 16, v183
	v_and_b32_e32 v165, 0xffff0000, v183
	v_mul_f32_e32 v158, 0xbfb8aa3b, v158
	v_mul_f32_e32 v159, 0xbfb8aa3b, v159
	v_mul_f32_e32 v160, 0xbfb8aa3b, v160
	v_mul_f32_e32 v161, 0xbfb8aa3b, v161
	v_mul_f32_e32 v162, 0xbfb8aa3b, v162
	v_mul_f32_e32 v163, 0xbfb8aa3b, v163
	v_mul_f32_e32 v164, 0xbfb8aa3b, v164
	v_mul_f32_e32 v165, 0xbfb8aa3b, v165
	v_exp_f32_e32 v158, v158
	v_exp_f32_e32 v159, v159
	v_exp_f32_e32 v160, v160
	v_exp_f32_e32 v161, v161
	v_exp_f32_e32 v162, v162
	v_exp_f32_e32 v163, v163
	v_exp_f32_e32 v164, v164
	v_exp_f32_e32 v165, v165
	v_add_f32_e32 v158, 1.0, v158
	v_add_f32_e32 v159, 1.0, v159
	v_add_f32_e32 v160, 1.0, v160
	v_add_f32_e32 v161, 1.0, v161
	v_add_f32_e32 v162, 1.0, v162
	v_add_f32_e32 v163, 1.0, v163
	v_add_f32_e32 v164, 1.0, v164
	v_add_f32_e32 v165, 1.0, v165
	v_rcp_f32_e32 v158, v158
	v_rcp_f32_e32 v159, v159
	v_rcp_f32_e32 v160, v160
	v_rcp_f32_e32 v161, v161
	v_rcp_f32_e32 v162, v162
	v_rcp_f32_e32 v163, v163
	v_rcp_f32_e32 v164, v164
	v_rcp_f32_e32 v165, v165
	s_nop 0
	v_pk_mul_f32 v[4:5], v[4:5], v[158:159]
	v_pk_mul_f32 v[6:7], v[6:7], v[160:161]
	v_pk_mul_f32 v[0:1], v[0:1], v[162:163]
	v_pk_mul_f32 v[2:3], v[2:3], v[164:165]
	v_cvt_pk_bf16_f32 v180, v4, v5
	v_cvt_pk_bf16_f32 v181, v6, v7
	v_cvt_pk_bf16_f32 v182, v0, v1
	v_cvt_pk_bf16_f32 v183, v2, v3
	global_store_dwordx4 v147, v[180:183], s[82:83] offset:256
	s_andn2_b64 vcc, exec, s[6:7]
	s_mov_b64 s[6:7], -1
	s_cbranch_vccnz .LBB0_1092
	s_andn2_b64 vcc, exec, s[0:1]
	s_cbranch_vccnz .LBB0_1091
	s_barrier
	s_branch .LBB0_1091

.LBB0_1127:
	v_lshl_add_u32 v128, s26, 8, v160
	v_lshl_or_b32 v129, s51, 8, v162
	s_add_u32 s52, s10, s16
	s_addc_u32 s53, s11, s17
	v_lshlrev_b32_e32 v129, 1, v129
	s_add_u32 s54, s52, 0x26000
	s_addc_u32 s55, s53, 0
	s_add_u32 s56, s52, 0x4c000
	s_addc_u32 s57, s53, 0
	s_add_u32 s58, s52, 0x72000
	s_addc_u32 s59, s53, 0
	s_add_u32 s60, s52, 0x130000
	s_addc_u32 s61, s53, 0
	s_add_u32 s62, s52, 0x156000
	s_addc_u32 s63, s53, 0
	s_add_u32 s66, s52, 0x17c000
	s_addc_u32 s67, s53, 0
	s_add_u32 s68, s52, 0x1a2000
	s_addc_u32 s69, s53, 0
	s_add_u32 s70, s8, 0x8000
	s_addc_u32 s71, s9, 0
	s_add_u32 s72, s8, 0x10000
	s_addc_u32 s73, s9, 0
	s_add_u32 s74, s8, 0x18000
	s_addc_u32 s75, s9, 0
	s_add_u32 s76, s8, 0x40000
	s_addc_u32 s77, s9, 0
	s_add_u32 s78, s8, 0x48000
	s_addc_u32 s79, s9, 0
	s_add_u32 s80, s8, 0x50000
	s_addc_u32 s81, s9, 0
	s_add_u32 s82, s8, 0x58000
	s_addc_u32 s83, s9, 0
	v_mad_u32_u24 v130, v128, s50, v129
	v_lshl_add_u32 v131, v128, 11, v129
	s_nop 1
	global_load_dwordx4 v[166:169], v130, s[52:53]
	global_load_dwordx4 v[170:173], v130, s[52:53] offset:256
	global_load_dwordx4 v[174:177], v130, s[54:55]
	global_load_dwordx4 v[178:181], v130, s[54:55] offset:256
	global_load_dwordx4 v[214:217], v131, s[8:9]
	global_load_dwordx4 v[218:221], v131, s[8:9] offset:256
	global_load_dwordx4 v[222:225], v131, s[70:71]
	global_load_dwordx4 v[226:229], v131, s[70:71] offset:256
	global_load_dwordx4 v[182:185], v130, s[56:57]
	global_load_dwordx4 v[186:189], v130, s[56:57] offset:256
	global_load_dwordx4 v[190:193], v130, s[58:59]
	global_load_dwordx4 v[194:197], v130, s[58:59] offset:256
	global_load_dwordx4 v[240:243], v131, s[72:73]
	global_load_dwordx4 v[244:247], v131, s[72:73] offset:256
	global_load_dwordx4 v[248:251], v131, s[74:75]
	global_load_dwordx4 v[156:159], v131, s[74:75] offset:256
	global_load_dwordx4 v[198:201], v130, s[60:61]
	global_load_dwordx4 v[202:205], v130, s[60:61] offset:256
	global_load_dwordx4 v[206:209], v130, s[62:63]
	global_load_dwordx4 v[210:213], v130, s[62:63] offset:256
	s_waitcnt vmcnt(12)
	v_lshlrev_b32_e32 v148, 16, v166
	v_and_b32_e32 v149, 0xffff0000, v166
	v_lshlrev_b32_e32 v150, 16, v167
	v_and_b32_e32 v151, 0xffff0000, v167
	v_lshlrev_b32_e32 v152, 16, v168
	v_and_b32_e32 v153, 0xffff0000, v168
	v_lshlrev_b32_e32 v154, 16, v169
	v_and_b32_e32 v155, 0xffff0000, v169
	v_mul_f32_e32 v148, 0xbfb8aa3b, v148
	v_mul_f32_e32 v149, 0xbfb8aa3b, v149
	v_mul_f32_e32 v150, 0xbfb8aa3b, v150
	v_mul_f32_e32 v151, 0xbfb8aa3b, v151
	v_mul_f32_e32 v152, 0xbfb8aa3b, v152
	v_mul_f32_e32 v153, 0xbfb8aa3b, v153
	v_mul_f32_e32 v154, 0xbfb8aa3b, v154
	v_mul_f32_e32 v155, 0xbfb8aa3b, v155
	v_exp_f32_e32 v148, v148
	v_exp_f32_e32 v149, v149
	v_exp_f32_e32 v150, v150
	v_exp_f32_e32 v151, v151
	v_exp_f32_e32 v152, v152
	v_exp_f32_e32 v153, v153
	v_exp_f32_e32 v154, v154
	v_exp_f32_e32 v155, v155
	v_lshlrev_b32_e32 v232, 16, v214
	v_and_b32_e32 v233, 0xffff0000, v214
	v_lshlrev_b32_e32 v234, 16, v215
	v_and_b32_e32 v235, 0xffff0000, v215
	v_lshlrev_b32_e32 v236, 16, v216
	v_and_b32_e32 v237, 0xffff0000, v216
	v_lshlrev_b32_e32 v238, 16, v217
	v_and_b32_e32 v239, 0xffff0000, v217
	v_add_f32_e32 v148, 1.0, v148
	v_add_f32_e32 v149, 1.0, v149
	v_add_f32_e32 v150, 1.0, v150
	v_add_f32_e32 v151, 1.0, v151
	v_add_f32_e32 v152, 1.0, v152
	v_add_f32_e32 v153, 1.0, v153
	v_add_f32_e32 v154, 1.0, v154
	v_add_f32_e32 v155, 1.0, v155
	v_rcp_f32_e32 v148, v148
	v_rcp_f32_e32 v149, v149
	v_rcp_f32_e32 v150, v150
	v_rcp_f32_e32 v151, v151
	v_rcp_f32_e32 v152, v152
	v_rcp_f32_e32 v153, v153
	v_rcp_f32_e32 v154, v154
	v_rcp_f32_e32 v155, v155
	s_nop 0
	v_pk_fma_f32 v[124:125], v[124:125], v[148:149], v[232:233]
	v_pk_fma_f32 v[126:127], v[126:127], v[150:151], v[234:235]
	v_pk_fma_f32 v[120:121], v[120:121], v[152:153], v[236:237]
	v_pk_fma_f32 v[122:123], v[122:123], v[154:155], v[238:239]
	v_cvt_pk_bf16_f32 v166, v124, v125
	v_cvt_pk_bf16_f32 v167, v126, v127
	v_cvt_pk_bf16_f32 v168, v120, v121
	v_cvt_pk_bf16_f32 v169, v122, v123
	global_store_dwordx4 v131, v[166:169], s[8:9]
	v_lshlrev_b32_e32 v148, 16, v170
	v_and_b32_e32 v149, 0xffff0000, v170
	v_lshlrev_b32_e32 v150, 16, v171
	v_and_b32_e32 v151, 0xffff0000, v171
	v_lshlrev_b32_e32 v152, 16, v172
	v_and_b32_e32 v153, 0xffff0000, v172
	v_lshlrev_b32_e32 v154, 16, v173
	v_and_b32_e32 v155, 0xffff0000, v173
	v_mul_f32_e32 v148, 0xbfb8aa3b, v148
	v_mul_f32_e32 v149, 0xbfb8aa3b, v149
	v_mul_f32_e32 v150, 0xbfb8aa3b, v150
	v_mul_f32_e32 v151, 0xbfb8aa3b, v151
	v_mul_f32_e32 v152, 0xbfb8aa3b, v152
	v_mul_f32_e32 v153, 0xbfb8aa3b, v153
	v_mul_f32_e32 v154, 0xbfb8aa3b, v154
	v_mul_f32_e32 v155, 0xbfb8aa3b, v155
	v_exp_f32_e32 v148, v148
	v_exp_f32_e32 v149, v149
	v_exp_f32_e32 v150, v150
	v_exp_f32_e32 v151, v151
	v_exp_f32_e32 v152, v152
	v_exp_f32_e32 v153, v153
	v_exp_f32_e32 v154, v154
	v_exp_f32_e32 v155, v155
	v_lshlrev_b32_e32 v232, 16, v218
	v_and_b32_e32 v233, 0xffff0000, v218
	v_lshlrev_b32_e32 v234, 16, v219
	v_and_b32_e32 v235, 0xffff0000, v219
	v_lshlrev_b32_e32 v236, 16, v220
	v_and_b32_e32 v237, 0xffff0000, v220
	v_lshlrev_b32_e32 v238, 16, v221
	v_and_b32_e32 v239, 0xffff0000, v221
	v_add_f32_e32 v148, 1.0, v148
	v_add_f32_e32 v149, 1.0, v149
	v_add_f32_e32 v150, 1.0, v150
	v_add_f32_e32 v151, 1.0, v151
	v_add_f32_e32 v152, 1.0, v152
	v_add_f32_e32 v153, 1.0, v153
	v_add_f32_e32 v154, 1.0, v154
	v_add_f32_e32 v155, 1.0, v155
	v_rcp_f32_e32 v148, v148
	v_rcp_f32_e32 v149, v149
	v_rcp_f32_e32 v150, v150
	v_rcp_f32_e32 v151, v151
	v_rcp_f32_e32 v152, v152
	v_rcp_f32_e32 v153, v153
	v_rcp_f32_e32 v154, v154
	v_rcp_f32_e32 v155, v155
	s_nop 0
	v_pk_fma_f32 v[116:117], v[116:117], v[148:149], v[232:233]
	v_pk_fma_f32 v[118:119], v[118:119], v[150:151], v[234:235]
	v_pk_fma_f32 v[112:113], v[112:113], v[152:153], v[236:237]
	v_pk_fma_f32 v[114:115], v[114:115], v[154:155], v[238:239]
	v_cvt_pk_bf16_f32 v170, v116, v117
	v_cvt_pk_bf16_f32 v171, v118, v119
	v_cvt_pk_bf16_f32 v172, v112, v113
	v_cvt_pk_bf16_f32 v173, v114, v115
	global_store_dwordx4 v131, v[170:173], s[8:9] offset:256
	v_lshlrev_b32_e32 v148, 16, v174
	v_and_b32_e32 v149, 0xffff0000, v174
	v_lshlrev_b32_e32 v150, 16, v175
	v_and_b32_e32 v151, 0xffff0000, v175
	v_lshlrev_b32_e32 v152, 16, v176
	v_and_b32_e32 v153, 0xffff0000, v176
	v_lshlrev_b32_e32 v154, 16, v177
	v_and_b32_e32 v155, 0xffff0000, v177
	v_mul_f32_e32 v148, 0xbfb8aa3b, v148
	v_mul_f32_e32 v149, 0xbfb8aa3b, v149
	v_mul_f32_e32 v150, 0xbfb8aa3b, v150
	v_mul_f32_e32 v151, 0xbfb8aa3b, v151
	v_mul_f32_e32 v152, 0xbfb8aa3b, v152
	v_mul_f32_e32 v153, 0xbfb8aa3b, v153
	v_mul_f32_e32 v154, 0xbfb8aa3b, v154
	v_mul_f32_e32 v155, 0xbfb8aa3b, v155
	v_exp_f32_e32 v148, v148
	v_exp_f32_e32 v149, v149
	v_exp_f32_e32 v150, v150
	v_exp_f32_e32 v151, v151
	v_exp_f32_e32 v152, v152
	v_exp_f32_e32 v153, v153
	v_exp_f32_e32 v154, v154
	v_exp_f32_e32 v155, v155
	v_lshlrev_b32_e32 v232, 16, v222
	v_and_b32_e32 v233, 0xffff0000, v222
	v_lshlrev_b32_e32 v234, 16, v223
	v_and_b32_e32 v235, 0xffff0000, v223
	v_lshlrev_b32_e32 v236, 16, v224
	v_and_b32_e32 v237, 0xffff0000, v224
	v_lshlrev_b32_e32 v238, 16, v225
	v_and_b32_e32 v239, 0xffff0000, v225
	v_add_f32_e32 v148, 1.0, v148
	v_add_f32_e32 v149, 1.0, v149
	v_add_f32_e32 v150, 1.0, v150
	v_add_f32_e32 v151, 1.0, v151
	v_add_f32_e32 v152, 1.0, v152
	v_add_f32_e32 v153, 1.0, v153
	v_add_f32_e32 v154, 1.0, v154
	v_add_f32_e32 v155, 1.0, v155
	v_rcp_f32_e32 v148, v148
	v_rcp_f32_e32 v149, v149
	v_rcp_f32_e32 v150, v150
	v_rcp_f32_e32 v151, v151
	v_rcp_f32_e32 v152, v152
	v_rcp_f32_e32 v153, v153
	v_rcp_f32_e32 v154, v154
	v_rcp_f32_e32 v155, v155
	s_nop 0
	v_pk_fma_f32 v[108:109], v[108:109], v[148:149], v[232:233]
	v_pk_fma_f32 v[110:111], v[110:111], v[150:151], v[234:235]
	v_pk_fma_f32 v[104:105], v[104:105], v[152:153], v[236:237]
	v_pk_fma_f32 v[106:107], v[106:107], v[154:155], v[238:239]
	v_cvt_pk_bf16_f32 v174, v108, v109
	v_cvt_pk_bf16_f32 v175, v110, v111
	v_cvt_pk_bf16_f32 v176, v104, v105
	v_cvt_pk_bf16_f32 v177, v106, v107
	global_store_dwordx4 v131, v[174:177], s[70:71]
	v_lshlrev_b32_e32 v148, 16, v178
	v_and_b32_e32 v149, 0xffff0000, v178
	v_lshlrev_b32_e32 v150, 16, v179
	v_and_b32_e32 v151, 0xffff0000, v179
	v_lshlrev_b32_e32 v152, 16, v180
	v_and_b32_e32 v153, 0xffff0000, v180
	v_lshlrev_b32_e32 v154, 16, v181
	v_and_b32_e32 v155, 0xffff0000, v181
	v_mul_f32_e32 v148, 0xbfb8aa3b, v148
	v_mul_f32_e32 v149, 0xbfb8aa3b, v149
	v_mul_f32_e32 v150, 0xbfb8aa3b, v150
	v_mul_f32_e32 v151, 0xbfb8aa3b, v151
	v_mul_f32_e32 v152, 0xbfb8aa3b, v152
	v_mul_f32_e32 v153, 0xbfb8aa3b, v153
	v_mul_f32_e32 v154, 0xbfb8aa3b, v154
	v_mul_f32_e32 v155, 0xbfb8aa3b, v155
	v_exp_f32_e32 v148, v148
	v_exp_f32_e32 v149, v149
	v_exp_f32_e32 v150, v150
	v_exp_f32_e32 v151, v151
	v_exp_f32_e32 v152, v152
	v_exp_f32_e32 v153, v153
	v_exp_f32_e32 v154, v154
	v_exp_f32_e32 v155, v155
	v_lshlrev_b32_e32 v232, 16, v226
	v_and_b32_e32 v233, 0xffff0000, v226
	v_lshlrev_b32_e32 v234, 16, v227
	v_and_b32_e32 v235, 0xffff0000, v227
	v_lshlrev_b32_e32 v236, 16, v228
	v_and_b32_e32 v237, 0xffff0000, v228
	v_lshlrev_b32_e32 v238, 16, v229
	v_and_b32_e32 v239, 0xffff0000, v229
	v_add_f32_e32 v148, 1.0, v148
	v_add_f32_e32 v149, 1.0, v149
	v_add_f32_e32 v150, 1.0, v150
	v_add_f32_e32 v151, 1.0, v151
	v_add_f32_e32 v152, 1.0, v152
	v_add_f32_e32 v153, 1.0, v153
	v_add_f32_e32 v154, 1.0, v154
	v_add_f32_e32 v155, 1.0, v155
	v_rcp_f32_e32 v148, v148
	v_rcp_f32_e32 v149, v149
	v_rcp_f32_e32 v150, v150
	v_rcp_f32_e32 v151, v151
	v_rcp_f32_e32 v152, v152
	v_rcp_f32_e32 v153, v153
	v_rcp_f32_e32 v154, v154
	v_rcp_f32_e32 v155, v155
	s_nop 0
	v_pk_fma_f32 v[100:101], v[100:101], v[148:149], v[232:233]
	v_pk_fma_f32 v[102:103], v[102:103], v[150:151], v[234:235]
	v_pk_fma_f32 v[96:97], v[96:97], v[152:153], v[236:237]
	v_pk_fma_f32 v[98:99], v[98:99], v[154:155], v[238:239]
	v_cvt_pk_bf16_f32 v178, v100, v101
	v_cvt_pk_bf16_f32 v179, v102, v103
	v_cvt_pk_bf16_f32 v180, v96, v97
	v_cvt_pk_bf16_f32 v181, v98, v99
	global_store_dwordx4 v131, v[178:181], s[70:71] offset:256
	s_nop 1
	global_load_dwordx4 v[214:217], v131, s[76:77]
	global_load_dwordx4 v[218:221], v131, s[76:77] offset:256
	global_load_dwordx4 v[222:225], v131, s[78:79]
	global_load_dwordx4 v[226:229], v131, s[78:79] offset:256
	global_load_dwordx4 v[166:169], v130, s[66:67]
	global_load_dwordx4 v[170:173], v130, s[66:67] offset:256
	global_load_dwordx4 v[174:177], v130, s[68:69]
	global_load_dwordx4 v[178:181], v130, s[68:69] offset:256
	s_waitcnt vmcnt(16)
	v_lshlrev_b32_e32 v148, 16, v182
	v_and_b32_e32 v149, 0xffff0000, v182
	v_lshlrev_b32_e32 v150, 16, v183
	v_and_b32_e32 v151, 0xffff0000, v183
	v_lshlrev_b32_e32 v152, 16, v184
	v_and_b32_e32 v153, 0xffff0000, v184
	v_lshlrev_b32_e32 v154, 16, v185
	v_and_b32_e32 v155, 0xffff0000, v185
	v_mul_f32_e32 v148, 0xbfb8aa3b, v148
	v_mul_f32_e32 v149, 0xbfb8aa3b, v149
	v_mul_f32_e32 v150, 0xbfb8aa3b, v150
	v_mul_f32_e32 v151, 0xbfb8aa3b, v151
	v_mul_f32_e32 v152, 0xbfb8aa3b, v152
	v_mul_f32_e32 v153, 0xbfb8aa3b, v153
	v_mul_f32_e32 v154, 0xbfb8aa3b, v154
	v_mul_f32_e32 v155, 0xbfb8aa3b, v155
	v_exp_f32_e32 v148, v148
	v_exp_f32_e32 v149, v149
	v_exp_f32_e32 v150, v150
	v_exp_f32_e32 v151, v151
	v_exp_f32_e32 v152, v152
	v_exp_f32_e32 v153, v153
	v_exp_f32_e32 v154, v154
	v_exp_f32_e32 v155, v155
	v_lshlrev_b32_e32 v232, 16, v240
	v_and_b32_e32 v233, 0xffff0000, v240
	v_lshlrev_b32_e32 v234, 16, v241
	v_and_b32_e32 v235, 0xffff0000, v241
	v_lshlrev_b32_e32 v236, 16, v242
	v_and_b32_e32 v237, 0xffff0000, v242
	v_lshlrev_b32_e32 v238, 16, v243
	v_and_b32_e32 v239, 0xffff0000, v243
	v_add_f32_e32 v148, 1.0, v148
	v_add_f32_e32 v149, 1.0, v149
	v_add_f32_e32 v150, 1.0, v150
	v_add_f32_e32 v151, 1.0, v151
	v_add_f32_e32 v152, 1.0, v152
	v_add_f32_e32 v153, 1.0, v153
	v_add_f32_e32 v154, 1.0, v154
	v_add_f32_e32 v155, 1.0, v155
	v_rcp_f32_e32 v148, v148
	v_rcp_f32_e32 v149, v149
	v_rcp_f32_e32 v150, v150
	v_rcp_f32_e32 v151, v151
	v_rcp_f32_e32 v152, v152
	v_rcp_f32_e32 v153, v153
	v_rcp_f32_e32 v154, v154
	v_rcp_f32_e32 v155, v155
	s_nop 0
	v_pk_fma_f32 v[92:93], v[92:93], v[148:149], v[232:233]
	v_pk_fma_f32 v[94:95], v[94:95], v[150:151], v[234:235]
	v_pk_fma_f32 v[88:89], v[88:89], v[152:153], v[236:237]
	v_pk_fma_f32 v[90:91], v[90:91], v[154:155], v[238:239]
	v_cvt_pk_bf16_f32 v182, v92, v93
	v_cvt_pk_bf16_f32 v183, v94, v95
	v_cvt_pk_bf16_f32 v184, v88, v89
	v_cvt_pk_bf16_f32 v185, v90, v91
	global_store_dwordx4 v131, v[182:185], s[72:73]
	v_lshlrev_b32_e32 v148, 16, v186
	v_and_b32_e32 v149, 0xffff0000, v186
	v_lshlrev_b32_e32 v150, 16, v187
	v_and_b32_e32 v151, 0xffff0000, v187
	v_lshlrev_b32_e32 v152, 16, v188
	v_and_b32_e32 v153, 0xffff0000, v188
	v_lshlrev_b32_e32 v154, 16, v189
	v_and_b32_e32 v155, 0xffff0000, v189
	v_mul_f32_e32 v148, 0xbfb8aa3b, v148
	v_mul_f32_e32 v149, 0xbfb8aa3b, v149
	v_mul_f32_e32 v150, 0xbfb8aa3b, v150
	v_mul_f32_e32 v151, 0xbfb8aa3b, v151
	v_mul_f32_e32 v152, 0xbfb8aa3b, v152
	v_mul_f32_e32 v153, 0xbfb8aa3b, v153
	v_mul_f32_e32 v154, 0xbfb8aa3b, v154
	v_mul_f32_e32 v155, 0xbfb8aa3b, v155
	v_exp_f32_e32 v148, v148
	v_exp_f32_e32 v149, v149
	v_exp_f32_e32 v150, v150
	v_exp_f32_e32 v151, v151
	v_exp_f32_e32 v152, v152
	v_exp_f32_e32 v153, v153
	v_exp_f32_e32 v154, v154
	v_exp_f32_e32 v155, v155
	v_lshlrev_b32_e32 v232, 16, v244
	v_and_b32_e32 v233, 0xffff0000, v244
	v_lshlrev_b32_e32 v234, 16, v245
	v_and_b32_e32 v235, 0xffff0000, v245
	v_lshlrev_b32_e32 v236, 16, v246
	v_and_b32_e32 v237, 0xffff0000, v246
	v_lshlrev_b32_e32 v238, 16, v247
	v_and_b32_e32 v239, 0xffff0000, v247
	v_add_f32_e32 v148, 1.0, v148
	v_add_f32_e32 v149, 1.0, v149
	v_add_f32_e32 v150, 1.0, v150
	v_add_f32_e32 v151, 1.0, v151
	v_add_f32_e32 v152, 1.0, v152
	v_add_f32_e32 v153, 1.0, v153
	v_add_f32_e32 v154, 1.0, v154
	v_add_f32_e32 v155, 1.0, v155
	v_rcp_f32_e32 v148, v148
	v_rcp_f32_e32 v149, v149
	v_rcp_f32_e32 v150, v150
	v_rcp_f32_e32 v151, v151
	v_rcp_f32_e32 v152, v152
	v_rcp_f32_e32 v153, v153
	v_rcp_f32_e32 v154, v154
	v_rcp_f32_e32 v155, v155
	s_nop 0
	v_pk_fma_f32 v[84:85], v[84:85], v[148:149], v[232:233]
	v_pk_fma_f32 v[86:87], v[86:87], v[150:151], v[234:235]
	v_pk_fma_f32 v[80:81], v[80:81], v[152:153], v[236:237]
	v_pk_fma_f32 v[82:83], v[82:83], v[154:155], v[238:239]
	v_cvt_pk_bf16_f32 v186, v84, v85
	v_cvt_pk_bf16_f32 v187, v86, v87
	v_cvt_pk_bf16_f32 v188, v80, v81
	v_cvt_pk_bf16_f32 v189, v82, v83
	global_store_dwordx4 v131, v[186:189], s[72:73] offset:256
	v_lshlrev_b32_e32 v148, 16, v190
	v_and_b32_e32 v149, 0xffff0000, v190
	v_lshlrev_b32_e32 v150, 16, v191
	v_and_b32_e32 v151, 0xffff0000, v191
	v_lshlrev_b32_e32 v152, 16, v192
	v_and_b32_e32 v153, 0xffff0000, v192
	v_lshlrev_b32_e32 v154, 16, v193
	v_and_b32_e32 v155, 0xffff0000, v193
	v_mul_f32_e32 v148, 0xbfb8aa3b, v148
	v_mul_f32_e32 v149, 0xbfb8aa3b, v149
	v_mul_f32_e32 v150, 0xbfb8aa3b, v150
	v_mul_f32_e32 v151, 0xbfb8aa3b, v151
	v_mul_f32_e32 v152, 0xbfb8aa3b, v152
	v_mul_f32_e32 v153, 0xbfb8aa3b, v153
	v_mul_f32_e32 v154, 0xbfb8aa3b, v154
	v_mul_f32_e32 v155, 0xbfb8aa3b, v155
	v_exp_f32_e32 v148, v148
	v_exp_f32_e32 v149, v149
	v_exp_f32_e32 v150, v150
	v_exp_f32_e32 v151, v151
	v_exp_f32_e32 v152, v152
	v_exp_f32_e32 v153, v153
	v_exp_f32_e32 v154, v154
	v_exp_f32_e32 v155, v155
	v_lshlrev_b32_e32 v232, 16, v248
	v_and_b32_e32 v233, 0xffff0000, v248
	v_lshlrev_b32_e32 v234, 16, v249
	v_and_b32_e32 v235, 0xffff0000, v249
	v_lshlrev_b32_e32 v236, 16, v250
	v_and_b32_e32 v237, 0xffff0000, v250
	v_lshlrev_b32_e32 v238, 16, v251
	v_and_b32_e32 v239, 0xffff0000, v251
	v_add_f32_e32 v148, 1.0, v148
	v_add_f32_e32 v149, 1.0, v149
	v_add_f32_e32 v150, 1.0, v150
	v_add_f32_e32 v151, 1.0, v151
	v_add_f32_e32 v152, 1.0, v152
	v_add_f32_e32 v153, 1.0, v153
	v_add_f32_e32 v154, 1.0, v154
	v_add_f32_e32 v155, 1.0, v155
	v_rcp_f32_e32 v148, v148
	v_rcp_f32_e32 v149, v149
	v_rcp_f32_e32 v150, v150
	v_rcp_f32_e32 v151, v151
	v_rcp_f32_e32 v152, v152
	v_rcp_f32_e32 v153, v153
	v_rcp_f32_e32 v154, v154
	v_rcp_f32_e32 v155, v155
	s_nop 0
	v_pk_fma_f32 v[76:77], v[76:77], v[148:149], v[232:233]
	v_pk_fma_f32 v[78:79], v[78:79], v[150:151], v[234:235]
	v_pk_fma_f32 v[72:73], v[72:73], v[152:153], v[236:237]
	v_pk_fma_f32 v[74:75], v[74:75], v[154:155], v[238:239]
	v_cvt_pk_bf16_f32 v190, v76, v77
	v_cvt_pk_bf16_f32 v191, v78, v79
	v_cvt_pk_bf16_f32 v192, v72, v73
	v_cvt_pk_bf16_f32 v193, v74, v75
	global_store_dwordx4 v131, v[190:193], s[74:75]
	v_lshlrev_b32_e32 v148, 16, v194
	v_and_b32_e32 v149, 0xffff0000, v194
	v_lshlrev_b32_e32 v150, 16, v195
	v_and_b32_e32 v151, 0xffff0000, v195
	v_lshlrev_b32_e32 v152, 16, v196
	v_and_b32_e32 v153, 0xffff0000, v196
	v_lshlrev_b32_e32 v154, 16, v197
	v_and_b32_e32 v155, 0xffff0000, v197
	v_mul_f32_e32 v148, 0xbfb8aa3b, v148
	v_mul_f32_e32 v149, 0xbfb8aa3b, v149
	v_mul_f32_e32 v150, 0xbfb8aa3b, v150
	v_mul_f32_e32 v151, 0xbfb8aa3b, v151
	v_mul_f32_e32 v152, 0xbfb8aa3b, v152
	v_mul_f32_e32 v153, 0xbfb8aa3b, v153
	v_mul_f32_e32 v154, 0xbfb8aa3b, v154
	v_mul_f32_e32 v155, 0xbfb8aa3b, v155
	v_exp_f32_e32 v148, v148
	v_exp_f32_e32 v149, v149
	v_exp_f32_e32 v150, v150
	v_exp_f32_e32 v151, v151
	v_exp_f32_e32 v152, v152
	v_exp_f32_e32 v153, v153
	v_exp_f32_e32 v154, v154
	v_exp_f32_e32 v155, v155
	v_lshlrev_b32_e32 v232, 16, v156
	v_and_b32_e32 v233, 0xffff0000, v156
	v_lshlrev_b32_e32 v234, 16, v157
	v_and_b32_e32 v235, 0xffff0000, v157
	v_lshlrev_b32_e32 v236, 16, v158
	v_and_b32_e32 v237, 0xffff0000, v158
	v_lshlrev_b32_e32 v238, 16, v159
	v_and_b32_e32 v239, 0xffff0000, v159
	v_add_f32_e32 v148, 1.0, v148
	v_add_f32_e32 v149, 1.0, v149
	v_add_f32_e32 v150, 1.0, v150
	v_add_f32_e32 v151, 1.0, v151
	v_add_f32_e32 v152, 1.0, v152
	v_add_f32_e32 v153, 1.0, v153
	v_add_f32_e32 v154, 1.0, v154
	v_add_f32_e32 v155, 1.0, v155
	v_rcp_f32_e32 v148, v148
	v_rcp_f32_e32 v149, v149
	v_rcp_f32_e32 v150, v150
	v_rcp_f32_e32 v151, v151
	v_rcp_f32_e32 v152, v152
	v_rcp_f32_e32 v153, v153
	v_rcp_f32_e32 v154, v154
	v_rcp_f32_e32 v155, v155
	s_nop 0
	v_pk_fma_f32 v[68:69], v[68:69], v[148:149], v[232:233]
	v_pk_fma_f32 v[70:71], v[70:71], v[150:151], v[234:235]
	v_pk_fma_f32 v[64:65], v[64:65], v[152:153], v[236:237]
	v_pk_fma_f32 v[66:67], v[66:67], v[154:155], v[238:239]
	v_cvt_pk_bf16_f32 v194, v68, v69
	v_cvt_pk_bf16_f32 v195, v70, v71
	v_cvt_pk_bf16_f32 v196, v64, v65
	v_cvt_pk_bf16_f32 v197, v66, v67
	global_store_dwordx4 v131, v[194:197], s[74:75] offset:256
	s_nop 1
	global_load_dwordx4 v[240:243], v131, s[80:81]
	global_load_dwordx4 v[244:247], v131, s[80:81] offset:256
	global_load_dwordx4 v[248:251], v131, s[82:83]
	global_load_dwordx4 v[156:159], v131, s[82:83] offset:256
	s_waitcnt vmcnt(12)
	v_lshlrev_b32_e32 v148, 16, v198
	v_and_b32_e32 v149, 0xffff0000, v198
	v_lshlrev_b32_e32 v150, 16, v199
	v_and_b32_e32 v151, 0xffff0000, v199
	v_lshlrev_b32_e32 v152, 16, v200
	v_and_b32_e32 v153, 0xffff0000, v200
	v_lshlrev_b32_e32 v154, 16, v201
	v_and_b32_e32 v155, 0xffff0000, v201
	v_mul_f32_e32 v148, 0xbfb8aa3b, v148
	v_mul_f32_e32 v149, 0xbfb8aa3b, v149
	v_mul_f32_e32 v150, 0xbfb8aa3b, v150
	v_mul_f32_e32 v151, 0xbfb8aa3b, v151
	v_mul_f32_e32 v152, 0xbfb8aa3b, v152
	v_mul_f32_e32 v153, 0xbfb8aa3b, v153
	v_mul_f32_e32 v154, 0xbfb8aa3b, v154
	v_mul_f32_e32 v155, 0xbfb8aa3b, v155
	v_exp_f32_e32 v148, v148
	v_exp_f32_e32 v149, v149
	v_exp_f32_e32 v150, v150
	v_exp_f32_e32 v151, v151
	v_exp_f32_e32 v152, v152
	v_exp_f32_e32 v153, v153
	v_exp_f32_e32 v154, v154
	v_exp_f32_e32 v155, v155
	v_lshlrev_b32_e32 v232, 16, v214
	v_and_b32_e32 v233, 0xffff0000, v214
	v_lshlrev_b32_e32 v234, 16, v215
	v_and_b32_e32 v235, 0xffff0000, v215
	v_lshlrev_b32_e32 v236, 16, v216
	v_and_b32_e32 v237, 0xffff0000, v216
	v_lshlrev_b32_e32 v238, 16, v217
	v_and_b32_e32 v239, 0xffff0000, v217
	v_add_f32_e32 v148, 1.0, v148
	v_add_f32_e32 v149, 1.0, v149
	v_add_f32_e32 v150, 1.0, v150
	v_add_f32_e32 v151, 1.0, v151
	v_add_f32_e32 v152, 1.0, v152
	v_add_f32_e32 v153, 1.0, v153
	v_add_f32_e32 v154, 1.0, v154
	v_add_f32_e32 v155, 1.0, v155
	v_rcp_f32_e32 v148, v148
	v_rcp_f32_e32 v149, v149
	v_rcp_f32_e32 v150, v150
	v_rcp_f32_e32 v151, v151
	v_rcp_f32_e32 v152, v152
	v_rcp_f32_e32 v153, v153
	v_rcp_f32_e32 v154, v154
	v_rcp_f32_e32 v155, v155
	s_nop 0
	v_pk_fma_f32 v[60:61], v[60:61], v[148:149], v[232:233]
	v_pk_fma_f32 v[62:63], v[62:63], v[150:151], v[234:235]
	v_pk_fma_f32 v[56:57], v[56:57], v[152:153], v[236:237]
	v_pk_fma_f32 v[58:59], v[58:59], v[154:155], v[238:239]
	v_cvt_pk_bf16_f32 v198, v60, v61
	v_cvt_pk_bf16_f32 v199, v62, v63
	v_cvt_pk_bf16_f32 v200, v56, v57
	v_cvt_pk_bf16_f32 v201, v58, v59
	global_store_dwordx4 v131, v[198:201], s[76:77]
	v_lshlrev_b32_e32 v148, 16, v202
	v_and_b32_e32 v149, 0xffff0000, v202
	v_lshlrev_b32_e32 v150, 16, v203
	v_and_b32_e32 v151, 0xffff0000, v203
	v_lshlrev_b32_e32 v152, 16, v204
	v_and_b32_e32 v153, 0xffff0000, v204
	v_lshlrev_b32_e32 v154, 16, v205
	v_and_b32_e32 v155, 0xffff0000, v205
	v_mul_f32_e32 v148, 0xbfb8aa3b, v148
	v_mul_f32_e32 v149, 0xbfb8aa3b, v149
	v_mul_f32_e32 v150, 0xbfb8aa3b, v150
	v_mul_f32_e32 v151, 0xbfb8aa3b, v151
	v_mul_f32_e32 v152, 0xbfb8aa3b, v152
	v_mul_f32_e32 v153, 0xbfb8aa3b, v153
	v_mul_f32_e32 v154, 0xbfb8aa3b, v154
	v_mul_f32_e32 v155, 0xbfb8aa3b, v155
	v_exp_f32_e32 v148, v148
	v_exp_f32_e32 v149, v149
	v_exp_f32_e32 v150, v150
	v_exp_f32_e32 v151, v151
	v_exp_f32_e32 v152, v152
	v_exp_f32_e32 v153, v153
	v_exp_f32_e32 v154, v154
	v_exp_f32_e32 v155, v155
	v_lshlrev_b32_e32 v232, 16, v218
	v_and_b32_e32 v233, 0xffff0000, v218
	v_lshlrev_b32_e32 v234, 16, v219
	v_and_b32_e32 v235, 0xffff0000, v219
	v_lshlrev_b32_e32 v236, 16, v220
	v_and_b32_e32 v237, 0xffff0000, v220
	v_lshlrev_b32_e32 v238, 16, v221
	v_and_b32_e32 v239, 0xffff0000, v221
	v_add_f32_e32 v148, 1.0, v148
	v_add_f32_e32 v149, 1.0, v149
	v_add_f32_e32 v150, 1.0, v150
	v_add_f32_e32 v151, 1.0, v151
	v_add_f32_e32 v152, 1.0, v152
	v_add_f32_e32 v153, 1.0, v153
	v_add_f32_e32 v154, 1.0, v154
	v_add_f32_e32 v155, 1.0, v155
	v_rcp_f32_e32 v148, v148
	v_rcp_f32_e32 v149, v149
	v_rcp_f32_e32 v150, v150
	v_rcp_f32_e32 v151, v151
	v_rcp_f32_e32 v152, v152
	v_rcp_f32_e32 v153, v153
	v_rcp_f32_e32 v154, v154
	v_rcp_f32_e32 v155, v155
	s_nop 0
	v_pk_fma_f32 v[52:53], v[52:53], v[148:149], v[232:233]
	v_pk_fma_f32 v[54:55], v[54:55], v[150:151], v[234:235]
	v_pk_fma_f32 v[48:49], v[48:49], v[152:153], v[236:237]
	v_pk_fma_f32 v[50:51], v[50:51], v[154:155], v[238:239]
	v_cvt_pk_bf16_f32 v202, v52, v53
	v_cvt_pk_bf16_f32 v203, v54, v55
	v_cvt_pk_bf16_f32 v204, v48, v49
	v_cvt_pk_bf16_f32 v205, v50, v51
	global_store_dwordx4 v131, v[202:205], s[76:77] offset:256
	v_lshlrev_b32_e32 v148, 16, v206
	v_and_b32_e32 v149, 0xffff0000, v206
	v_lshlrev_b32_e32 v150, 16, v207
	v_and_b32_e32 v151, 0xffff0000, v207
	v_lshlrev_b32_e32 v152, 16, v208
	v_and_b32_e32 v153, 0xffff0000, v208
	v_lshlrev_b32_e32 v154, 16, v209
	v_and_b32_e32 v155, 0xffff0000, v209
	v_mul_f32_e32 v148, 0xbfb8aa3b, v148
	v_mul_f32_e32 v149, 0xbfb8aa3b, v149
	v_mul_f32_e32 v150, 0xbfb8aa3b, v150
	v_mul_f32_e32 v151, 0xbfb8aa3b, v151
	v_mul_f32_e32 v152, 0xbfb8aa3b, v152
	v_mul_f32_e32 v153, 0xbfb8aa3b, v153
	v_mul_f32_e32 v154, 0xbfb8aa3b, v154
	v_mul_f32_e32 v155, 0xbfb8aa3b, v155
	v_exp_f32_e32 v148, v148
	v_exp_f32_e32 v149, v149
	v_exp_f32_e32 v150, v150
	v_exp_f32_e32 v151, v151
	v_exp_f32_e32 v152, v152
	v_exp_f32_e32 v153, v153
	v_exp_f32_e32 v154, v154
	v_exp_f32_e32 v155, v155
	v_lshlrev_b32_e32 v232, 16, v222
	v_and_b32_e32 v233, 0xffff0000, v222
	v_lshlrev_b32_e32 v234, 16, v223
	v_and_b32_e32 v235, 0xffff0000, v223
	v_lshlrev_b32_e32 v236, 16, v224
	v_and_b32_e32 v237, 0xffff0000, v224
	v_lshlrev_b32_e32 v238, 16, v225
	v_and_b32_e32 v239, 0xffff0000, v225
	v_add_f32_e32 v148, 1.0, v148
	v_add_f32_e32 v149, 1.0, v149
	v_add_f32_e32 v150, 1.0, v150
	v_add_f32_e32 v151, 1.0, v151
	v_add_f32_e32 v152, 1.0, v152
	v_add_f32_e32 v153, 1.0, v153
	v_add_f32_e32 v154, 1.0, v154
	v_add_f32_e32 v155, 1.0, v155
	v_rcp_f32_e32 v148, v148
	v_rcp_f32_e32 v149, v149
	v_rcp_f32_e32 v150, v150
	v_rcp_f32_e32 v151, v151
	v_rcp_f32_e32 v152, v152
	v_rcp_f32_e32 v153, v153
	v_rcp_f32_e32 v154, v154
	v_rcp_f32_e32 v155, v155
	s_nop 0
	v_pk_fma_f32 v[44:45], v[44:45], v[148:149], v[232:233]
	v_pk_fma_f32 v[46:47], v[46:47], v[150:151], v[234:235]
	v_pk_fma_f32 v[40:41], v[40:41], v[152:153], v[236:237]
	v_pk_fma_f32 v[42:43], v[42:43], v[154:155], v[238:239]
	v_cvt_pk_bf16_f32 v206, v44, v45
	v_cvt_pk_bf16_f32 v207, v46, v47
	v_cvt_pk_bf16_f32 v208, v40, v41
	v_cvt_pk_bf16_f32 v209, v42, v43
	global_store_dwordx4 v131, v[206:209], s[78:79]
	v_lshlrev_b32_e32 v148, 16, v210
	v_and_b32_e32 v149, 0xffff0000, v210
	v_lshlrev_b32_e32 v150, 16, v211
	v_and_b32_e32 v151, 0xffff0000, v211
	v_lshlrev_b32_e32 v152, 16, v212
	v_and_b32_e32 v153, 0xffff0000, v212
	v_lshlrev_b32_e32 v154, 16, v213
	v_and_b32_e32 v155, 0xffff0000, v213
	v_mul_f32_e32 v148, 0xbfb8aa3b, v148
	v_mul_f32_e32 v149, 0xbfb8aa3b, v149
	v_mul_f32_e32 v150, 0xbfb8aa3b, v150
	v_mul_f32_e32 v151, 0xbfb8aa3b, v151
	v_mul_f32_e32 v152, 0xbfb8aa3b, v152
	v_mul_f32_e32 v153, 0xbfb8aa3b, v153
	v_mul_f32_e32 v154, 0xbfb8aa3b, v154
	v_mul_f32_e32 v155, 0xbfb8aa3b, v155
	v_exp_f32_e32 v148, v148
	v_exp_f32_e32 v149, v149
	v_exp_f32_e32 v150, v150
	v_exp_f32_e32 v151, v151
	v_exp_f32_e32 v152, v152
	v_exp_f32_e32 v153, v153
	v_exp_f32_e32 v154, v154
	v_exp_f32_e32 v155, v155
	v_lshlrev_b32_e32 v232, 16, v226
	v_and_b32_e32 v233, 0xffff0000, v226
	v_lshlrev_b32_e32 v234, 16, v227
	v_and_b32_e32 v235, 0xffff0000, v227
	v_lshlrev_b32_e32 v236, 16, v228
	v_and_b32_e32 v237, 0xffff0000, v228
	v_lshlrev_b32_e32 v238, 16, v229
	v_and_b32_e32 v239, 0xffff0000, v229
	v_add_f32_e32 v148, 1.0, v148
	v_add_f32_e32 v149, 1.0, v149
	v_add_f32_e32 v150, 1.0, v150
	v_add_f32_e32 v151, 1.0, v151
	v_add_f32_e32 v152, 1.0, v152
	v_add_f32_e32 v153, 1.0, v153
	v_add_f32_e32 v154, 1.0, v154
	v_add_f32_e32 v155, 1.0, v155
	v_rcp_f32_e32 v148, v148
	v_rcp_f32_e32 v149, v149
	v_rcp_f32_e32 v150, v150
	v_rcp_f32_e32 v151, v151
	v_rcp_f32_e32 v152, v152
	v_rcp_f32_e32 v153, v153
	v_rcp_f32_e32 v154, v154
	v_rcp_f32_e32 v155, v155
	s_nop 0
	v_pk_fma_f32 v[36:37], v[36:37], v[148:149], v[232:233]
	v_pk_fma_f32 v[38:39], v[38:39], v[150:151], v[234:235]
	v_pk_fma_f32 v[32:33], v[32:33], v[152:153], v[236:237]
	v_pk_fma_f32 v[34:35], v[34:35], v[154:155], v[238:239]
	v_cvt_pk_bf16_f32 v210, v36, v37
	v_cvt_pk_bf16_f32 v211, v38, v39
	v_cvt_pk_bf16_f32 v212, v32, v33
	v_cvt_pk_bf16_f32 v213, v34, v35
	global_store_dwordx4 v131, v[210:213], s[78:79] offset:256
	s_waitcnt vmcnt(4)
	v_lshlrev_b32_e32 v148, 16, v166
	v_and_b32_e32 v149, 0xffff0000, v166
	v_lshlrev_b32_e32 v150, 16, v167
	v_and_b32_e32 v151, 0xffff0000, v167
	v_lshlrev_b32_e32 v152, 16, v168
	v_and_b32_e32 v153, 0xffff0000, v168
	v_lshlrev_b32_e32 v154, 16, v169
	v_and_b32_e32 v155, 0xffff0000, v169
	v_mul_f32_e32 v148, 0xbfb8aa3b, v148
	v_mul_f32_e32 v149, 0xbfb8aa3b, v149
	v_mul_f32_e32 v150, 0xbfb8aa3b, v150
	v_mul_f32_e32 v151, 0xbfb8aa3b, v151
	v_mul_f32_e32 v152, 0xbfb8aa3b, v152
	v_mul_f32_e32 v153, 0xbfb8aa3b, v153
	v_mul_f32_e32 v154, 0xbfb8aa3b, v154
	v_mul_f32_e32 v155, 0xbfb8aa3b, v155
	v_exp_f32_e32 v148, v148
	v_exp_f32_e32 v149, v149
	v_exp_f32_e32 v150, v150
	v_exp_f32_e32 v151, v151
	v_exp_f32_e32 v152, v152
	v_exp_f32_e32 v153, v153
	v_exp_f32_e32 v154, v154
	v_exp_f32_e32 v155, v155
	v_lshlrev_b32_e32 v232, 16, v240
	v_and_b32_e32 v233, 0xffff0000, v240
	v_lshlrev_b32_e32 v234, 16, v241
	v_and_b32_e32 v235, 0xffff0000, v241
	v_lshlrev_b32_e32 v236, 16, v242
	v_and_b32_e32 v237, 0xffff0000, v242
	v_lshlrev_b32_e32 v238, 16, v243
	v_and_b32_e32 v239, 0xffff0000, v243
	v_add_f32_e32 v148, 1.0, v148
	v_add_f32_e32 v149, 1.0, v149
	v_add_f32_e32 v150, 1.0, v150
	v_add_f32_e32 v151, 1.0, v151
	v_add_f32_e32 v152, 1.0, v152
	v_add_f32_e32 v153, 1.0, v153
	v_add_f32_e32 v154, 1.0, v154
	v_add_f32_e32 v155, 1.0, v155
	v_rcp_f32_e32 v148, v148
	v_rcp_f32_e32 v149, v149
	v_rcp_f32_e32 v150, v150
	v_rcp_f32_e32 v151, v151
	v_rcp_f32_e32 v152, v152
	v_rcp_f32_e32 v153, v153
	v_rcp_f32_e32 v154, v154
	v_rcp_f32_e32 v155, v155
	s_nop 0
	v_pk_fma_f32 v[28:29], v[28:29], v[148:149], v[232:233]
	v_pk_fma_f32 v[30:31], v[30:31], v[150:151], v[234:235]
	v_pk_fma_f32 v[24:25], v[24:25], v[152:153], v[236:237]
	v_pk_fma_f32 v[26:27], v[26:27], v[154:155], v[238:239]
	v_cvt_pk_bf16_f32 v166, v28, v29
	v_cvt_pk_bf16_f32 v167, v30, v31
	v_cvt_pk_bf16_f32 v168, v24, v25
	v_cvt_pk_bf16_f32 v169, v26, v27
	global_store_dwordx4 v131, v[166:169], s[80:81]
	v_lshlrev_b32_e32 v148, 16, v170
	v_and_b32_e32 v149, 0xffff0000, v170
	v_lshlrev_b32_e32 v150, 16, v171
	v_and_b32_e32 v151, 0xffff0000, v171
	v_lshlrev_b32_e32 v152, 16, v172
	v_and_b32_e32 v153, 0xffff0000, v172
	v_lshlrev_b32_e32 v154, 16, v173
	v_and_b32_e32 v155, 0xffff0000, v173
	v_mul_f32_e32 v148, 0xbfb8aa3b, v148
	v_mul_f32_e32 v149, 0xbfb8aa3b, v149
	v_mul_f32_e32 v150, 0xbfb8aa3b, v150
	v_mul_f32_e32 v151, 0xbfb8aa3b, v151
	v_mul_f32_e32 v152, 0xbfb8aa3b, v152
	v_mul_f32_e32 v153, 0xbfb8aa3b, v153
	v_mul_f32_e32 v154, 0xbfb8aa3b, v154
	v_mul_f32_e32 v155, 0xbfb8aa3b, v155
	v_exp_f32_e32 v148, v148
	v_exp_f32_e32 v149, v149
	v_exp_f32_e32 v150, v150
	v_exp_f32_e32 v151, v151
	v_exp_f32_e32 v152, v152
	v_exp_f32_e32 v153, v153
	v_exp_f32_e32 v154, v154
	v_exp_f32_e32 v155, v155
	v_lshlrev_b32_e32 v232, 16, v244
	v_and_b32_e32 v233, 0xffff0000, v244
	v_lshlrev_b32_e32 v234, 16, v245
	v_and_b32_e32 v235, 0xffff0000, v245
	v_lshlrev_b32_e32 v236, 16, v246
	v_and_b32_e32 v237, 0xffff0000, v246
	v_lshlrev_b32_e32 v238, 16, v247
	v_and_b32_e32 v239, 0xffff0000, v247
	v_add_f32_e32 v148, 1.0, v148
	v_add_f32_e32 v149, 1.0, v149
	v_add_f32_e32 v150, 1.0, v150
	v_add_f32_e32 v151, 1.0, v151
	v_add_f32_e32 v152, 1.0, v152
	v_add_f32_e32 v153, 1.0, v153
	v_add_f32_e32 v154, 1.0, v154
	v_add_f32_e32 v155, 1.0, v155
	v_rcp_f32_e32 v148, v148
	v_rcp_f32_e32 v149, v149
	v_rcp_f32_e32 v150, v150
	v_rcp_f32_e32 v151, v151
	v_rcp_f32_e32 v152, v152
	v_rcp_f32_e32 v153, v153
	v_rcp_f32_e32 v154, v154
	v_rcp_f32_e32 v155, v155
	s_nop 0
	v_pk_fma_f32 v[20:21], v[20:21], v[148:149], v[232:233]
	v_pk_fma_f32 v[22:23], v[22:23], v[150:151], v[234:235]
	v_pk_fma_f32 v[16:17], v[16:17], v[152:153], v[236:237]
	v_pk_fma_f32 v[18:19], v[18:19], v[154:155], v[238:239]
	v_cvt_pk_bf16_f32 v170, v20, v21
	v_cvt_pk_bf16_f32 v171, v22, v23
	v_cvt_pk_bf16_f32 v172, v16, v17
	v_cvt_pk_bf16_f32 v173, v18, v19
	global_store_dwordx4 v131, v[170:173], s[80:81] offset:256
	v_lshlrev_b32_e32 v148, 16, v174
	v_and_b32_e32 v149, 0xffff0000, v174
	v_lshlrev_b32_e32 v150, 16, v175
	v_and_b32_e32 v151, 0xffff0000, v175
	v_lshlrev_b32_e32 v152, 16, v176
	v_and_b32_e32 v153, 0xffff0000, v176
	v_lshlrev_b32_e32 v154, 16, v177
	v_and_b32_e32 v155, 0xffff0000, v177
	v_mul_f32_e32 v148, 0xbfb8aa3b, v148
	v_mul_f32_e32 v149, 0xbfb8aa3b, v149
	v_mul_f32_e32 v150, 0xbfb8aa3b, v150
	v_mul_f32_e32 v151, 0xbfb8aa3b, v151
	v_mul_f32_e32 v152, 0xbfb8aa3b, v152
	v_mul_f32_e32 v153, 0xbfb8aa3b, v153
	v_mul_f32_e32 v154, 0xbfb8aa3b, v154
	v_mul_f32_e32 v155, 0xbfb8aa3b, v155
	v_exp_f32_e32 v148, v148
	v_exp_f32_e32 v149, v149
	v_exp_f32_e32 v150, v150
	v_exp_f32_e32 v151, v151
	v_exp_f32_e32 v152, v152
	v_exp_f32_e32 v153, v153
	v_exp_f32_e32 v154, v154
	v_exp_f32_e32 v155, v155
	v_lshlrev_b32_e32 v232, 16, v248
	v_and_b32_e32 v233, 0xffff0000, v248
	v_lshlrev_b32_e32 v234, 16, v249
	v_and_b32_e32 v235, 0xffff0000, v249
	v_lshlrev_b32_e32 v236, 16, v250
	v_and_b32_e32 v237, 0xffff0000, v250
	v_lshlrev_b32_e32 v238, 16, v251
	v_and_b32_e32 v239, 0xffff0000, v251
	v_add_f32_e32 v148, 1.0, v148
	v_add_f32_e32 v149, 1.0, v149
	v_add_f32_e32 v150, 1.0, v150
	v_add_f32_e32 v151, 1.0, v151
	v_add_f32_e32 v152, 1.0, v152
	v_add_f32_e32 v153, 1.0, v153
	v_add_f32_e32 v154, 1.0, v154
	v_add_f32_e32 v155, 1.0, v155
	v_rcp_f32_e32 v148, v148
	v_rcp_f32_e32 v149, v149
	v_rcp_f32_e32 v150, v150
	v_rcp_f32_e32 v151, v151
	v_rcp_f32_e32 v152, v152
	v_rcp_f32_e32 v153, v153
	v_rcp_f32_e32 v154, v154
	v_rcp_f32_e32 v155, v155
	s_nop 0
	v_pk_fma_f32 v[12:13], v[12:13], v[148:149], v[232:233]
	v_pk_fma_f32 v[14:15], v[14:15], v[150:151], v[234:235]
	v_pk_fma_f32 v[8:9], v[8:9], v[152:153], v[236:237]
	v_pk_fma_f32 v[10:11], v[10:11], v[154:155], v[238:239]
	v_cvt_pk_bf16_f32 v174, v12, v13
	v_cvt_pk_bf16_f32 v175, v14, v15
	v_cvt_pk_bf16_f32 v176, v8, v9
	v_cvt_pk_bf16_f32 v177, v10, v11
	global_store_dwordx4 v131, v[174:177], s[82:83]
	v_lshlrev_b32_e32 v148, 16, v178
	v_and_b32_e32 v149, 0xffff0000, v178
	v_lshlrev_b32_e32 v150, 16, v179
	v_and_b32_e32 v151, 0xffff0000, v179
	v_lshlrev_b32_e32 v152, 16, v180
	v_and_b32_e32 v153, 0xffff0000, v180
	v_lshlrev_b32_e32 v154, 16, v181
	v_and_b32_e32 v155, 0xffff0000, v181
	v_mul_f32_e32 v148, 0xbfb8aa3b, v148
	v_mul_f32_e32 v149, 0xbfb8aa3b, v149
	v_mul_f32_e32 v150, 0xbfb8aa3b, v150
	v_mul_f32_e32 v151, 0xbfb8aa3b, v151
	v_mul_f32_e32 v152, 0xbfb8aa3b, v152
	v_mul_f32_e32 v153, 0xbfb8aa3b, v153
	v_mul_f32_e32 v154, 0xbfb8aa3b, v154
	v_mul_f32_e32 v155, 0xbfb8aa3b, v155
	v_exp_f32_e32 v148, v148
	v_exp_f32_e32 v149, v149
	v_exp_f32_e32 v150, v150
	v_exp_f32_e32 v151, v151
	v_exp_f32_e32 v152, v152
	v_exp_f32_e32 v153, v153
	v_exp_f32_e32 v154, v154
	v_exp_f32_e32 v155, v155
	v_lshlrev_b32_e32 v232, 16, v156
	v_and_b32_e32 v233, 0xffff0000, v156
	v_lshlrev_b32_e32 v234, 16, v157
	v_and_b32_e32 v235, 0xffff0000, v157
	v_lshlrev_b32_e32 v236, 16, v158
	v_and_b32_e32 v237, 0xffff0000, v158
	v_lshlrev_b32_e32 v238, 16, v159
	v_and_b32_e32 v239, 0xffff0000, v159
	v_add_f32_e32 v148, 1.0, v148
	v_add_f32_e32 v149, 1.0, v149
	v_add_f32_e32 v150, 1.0, v150
	v_add_f32_e32 v151, 1.0, v151
	v_add_f32_e32 v152, 1.0, v152
	v_add_f32_e32 v153, 1.0, v153
	v_add_f32_e32 v154, 1.0, v154
	v_add_f32_e32 v155, 1.0, v155
	v_rcp_f32_e32 v148, v148
	v_rcp_f32_e32 v149, v149
	v_rcp_f32_e32 v150, v150
	v_rcp_f32_e32 v151, v151
	v_rcp_f32_e32 v152, v152
	v_rcp_f32_e32 v153, v153
	v_rcp_f32_e32 v154, v154
	v_rcp_f32_e32 v155, v155
	s_nop 0
	v_pk_fma_f32 v[4:5], v[4:5], v[148:149], v[232:233]
	v_pk_fma_f32 v[6:7], v[6:7], v[150:151], v[234:235]
	v_pk_fma_f32 v[0:1], v[0:1], v[152:153], v[236:237]
	v_pk_fma_f32 v[2:3], v[2:3], v[154:155], v[238:239]
	v_cvt_pk_bf16_f32 v178, v4, v5
	v_cvt_pk_bf16_f32 v179, v6, v7
	v_cvt_pk_bf16_f32 v180, v0, v1
	v_cvt_pk_bf16_f32 v181, v2, v3
	global_store_dwordx4 v131, v[178:181], s[82:83] offset:256
	s_andn2_b64 vcc, exec, s[6:7]
	s_mov_b64 s[6:7], -1
	s_cbranch_vccnz .LBB0_1116
	s_andn2_b64 vcc, exec, s[0:1]
	s_cbranch_vccnz .LBB0_1115
	s_barrier
	s_branch .LBB0_1115
